# E34: DMA-first load segments: in all six K-loops the LDS-DMA pieces of a segment are issued before the segment's ds_read fragment reads
# baseline (speedup 1.0000x reference)
.Lcm1_skip:
.LBB0_225:
	s_add_u32 s36, s22, 0xfff80080
	s_addc_u32 s37, s23, -1
	s_cmp_eq_u32 s78, 28
	s_cselect_b32 s81, s5, s37
	s_cselect_b32 s80, s14, s36
	s_cselect_b32 vcc_hi, s20, s45
	s_cselect_b32 vcc_lo, s21, s24
	s_add_i32 m0, s77, 0xc000
	s_nop 0
	global_load_lds_dwordx4 v140, s[22:23]
	s_add_i32 m0, s77, 0xe000
	s_nop 0
	s_add_u32 s98, s22, s6
	s_addc_u32 s99, s23, s7
	global_load_lds_dwordx4 v140, s[98:99]
	ds_read_b128 v[128:131], v157
	ds_read_b128 v[132:135], v157 offset:1024
	ds_read_b128 v[146:149], v157 offset:2048
	ds_read_b128 v[164:167], v157 offset:3072
	ds_read_b128 v[168:171], v159
	ds_read_b128 v[172:175], v159 offset:1024
	ds_read_b128 v[176:179], v159 offset:2048
	ds_read_b128 v[180:183], v159 offset:3072
	ds_read_b128 v[184:187], v161
	ds_read_b128 v[188:191], v161 offset:1024
	ds_read_b128 v[192:195], v161 offset:2048
	ds_read_b128 v[196:199], v161 offset:3072
	ds_read_b128 v[200:203], v161 offset:4096
	ds_read_b128 v[204:207], v161 offset:5120
	ds_read_b128 v[208:211], v161 offset:6144
	ds_read_b128 v[212:215], v161 offset:7168
	s_waitcnt vmcnt(8)
	s_waitcnt lgkmcnt(0)
	s_barrier
	s_setprio 1
	s_waitcnt lgkmcnt(0)
	v_mfma_i32_16x16x64_i8 v[0:3], v[128:131], v[184:187], v[0:3]
	v_mfma_i32_16x16x64_i8 v[0:3], v[132:135], v[188:191], v[0:3]
	v_mfma_i32_16x16x64_i8 v[56:59], v[146:149], v[184:187], v[56:59]
	v_mfma_i32_16x16x64_i8 v[56:59], v[164:167], v[188:191], v[56:59]
	v_mfma_i32_16x16x64_i8 v[4:7], v[128:131], v[192:195], v[4:7]
	v_mfma_i32_16x16x64_i8 v[4:7], v[132:135], v[196:199], v[4:7]
	v_mfma_i32_16x16x64_i8 v[52:55], v[146:149], v[192:195], v[52:55]
	v_mfma_i32_16x16x64_i8 v[52:55], v[164:167], v[196:199], v[52:55]
	v_mfma_i32_16x16x64_i8 v[12:15], v[128:131], v[200:203], v[12:15]
	v_mfma_i32_16x16x64_i8 v[12:15], v[132:135], v[204:207], v[12:15]
	v_mfma_i32_16x16x64_i8 v[48:51], v[146:149], v[200:203], v[48:51]
	v_mfma_i32_16x16x64_i8 v[48:51], v[164:167], v[204:207], v[48:51]
	v_mfma_i32_16x16x64_i8 v[8:11], v[128:131], v[208:211], v[8:11]
	v_mfma_i32_16x16x64_i8 v[8:11], v[132:135], v[212:215], v[8:11]
	v_mfma_i32_16x16x64_i8 v[44:47], v[146:149], v[208:211], v[44:47]
	v_mfma_i32_16x16x64_i8 v[44:47], v[164:167], v[212:215], v[44:47]
	s_setprio 0
	s_setprio 1
	v_mfma_i32_16x16x64_i8 v[88:91], v[168:171], v[184:187], v[88:91]
	v_mfma_i32_16x16x64_i8 v[88:91], v[172:175], v[188:191], v[88:91]
	v_mfma_i32_16x16x64_i8 v[120:123], v[176:179], v[184:187], v[120:123]
	v_mfma_i32_16x16x64_i8 v[120:123], v[180:183], v[188:191], v[120:123]
	v_mfma_i32_16x16x64_i8 v[84:87], v[168:171], v[192:195], v[84:87]
	v_mfma_i32_16x16x64_i8 v[84:87], v[172:175], v[196:199], v[84:87]
	v_mfma_i32_16x16x64_i8 v[116:119], v[176:179], v[192:195], v[116:119]
	v_mfma_i32_16x16x64_i8 v[116:119], v[180:183], v[196:199], v[116:119]
	v_mfma_i32_16x16x64_i8 v[80:83], v[168:171], v[200:203], v[80:83]
	v_mfma_i32_16x16x64_i8 v[80:83], v[172:175], v[204:207], v[80:83]
	v_mfma_i32_16x16x64_i8 v[112:115], v[176:179], v[200:203], v[112:115]
	v_mfma_i32_16x16x64_i8 v[112:115], v[180:183], v[204:207], v[112:115]
	s_setprio 2
	s_barrier
	v_mfma_i32_16x16x64_i8 v[76:79], v[168:171], v[208:211], v[76:79]
	v_mfma_i32_16x16x64_i8 v[76:79], v[172:175], v[212:215], v[76:79]
	v_mfma_i32_16x16x64_i8 v[108:111], v[176:179], v[208:211], v[108:111]
	v_mfma_i32_16x16x64_i8 v[108:111], v[180:183], v[212:215], v[108:111]
	s_setprio 0
	s_add_i32 s36, s86, s63
	s_mov_b32 m0, s36
	s_nop 0
	global_load_lds_dwordx4 v138, vcc
	s_add_i32 m0, s36, 0x2000
	s_add_i32 s36, s87, s63
	s_add_u32 s98, vcc_lo, s6
	s_addc_u32 s99, vcc_hi, s7
	global_load_lds_dwordx4 v138, s[98:99]
	s_mov_b32 m0, s36
	s_nop 0
	s_add_u32 s98, vcc_lo, s8
	s_addc_u32 s99, vcc_hi, s9
	global_load_lds_dwordx4 v138, s[98:99]
	s_add_i32 m0, s36, 0x2000
	s_nop 0
	s_add_u32 s98, vcc_lo, s10
	s_addc_u32 s99, vcc_hi, s11
	global_load_lds_dwordx4 v138, s[98:99]
	s_mov_b32 m0, s77
	s_nop 0
	global_load_lds_dwordx4 v136, s[80:81]
	s_mov_b32 m0, s97
	s_nop 0
	s_add_u32 s98, s80, s6
	s_addc_u32 s99, s81, s7
	global_load_lds_dwordx4 v136, s[98:99]
	ds_read_b128 v[184:187], v161 offset:16384
	ds_read_b128 v[188:191], v161 offset:17408
	ds_read_b128 v[192:195], v161 offset:18432
	ds_read_b128 v[196:199], v161 offset:19456
	ds_read_b128 v[200:203], v161 offset:20480
	ds_read_b128 v[204:207], v161 offset:21504
	ds_read_b128 v[208:211], v161 offset:22528
	ds_read_b128 v[212:215], v161 offset:23552
	s_waitcnt vmcnt(8)
	s_waitcnt lgkmcnt(0)
	s_barrier
	s_setprio 1
	s_waitcnt lgkmcnt(0)
	v_mfma_i32_16x16x64_i8 v[20:23], v[128:131], v[184:187], v[20:23]
	v_mfma_i32_16x16x64_i8 v[20:23], v[132:135], v[188:191], v[20:23]
	v_mfma_i32_16x16x64_i8 v[40:43], v[146:149], v[184:187], v[40:43]
	v_mfma_i32_16x16x64_i8 v[40:43], v[164:167], v[188:191], v[40:43]
	v_mfma_i32_16x16x64_i8 v[16:19], v[128:131], v[192:195], v[16:19]
	v_mfma_i32_16x16x64_i8 v[16:19], v[132:135], v[196:199], v[16:19]
	v_mfma_i32_16x16x64_i8 v[36:39], v[146:149], v[192:195], v[36:39]
	v_mfma_i32_16x16x64_i8 v[36:39], v[164:167], v[196:199], v[36:39]
	v_mfma_i32_16x16x64_i8 v[24:27], v[128:131], v[200:203], v[24:27]
	v_mfma_i32_16x16x64_i8 v[24:27], v[132:135], v[204:207], v[24:27]
	v_mfma_i32_16x16x64_i8 v[32:35], v[146:149], v[200:203], v[32:35]
	v_mfma_i32_16x16x64_i8 v[32:35], v[164:167], v[204:207], v[32:35]
	v_mfma_i32_16x16x64_i8 v[28:31], v[128:131], v[208:211], v[28:31]
	v_mfma_i32_16x16x64_i8 v[28:31], v[132:135], v[212:215], v[28:31]
	v_mfma_i32_16x16x64_i8 v[60:63], v[146:149], v[208:211], v[60:63]
	v_mfma_i32_16x16x64_i8 v[60:63], v[164:167], v[212:215], v[60:63]
	s_setprio 0
	s_setprio 1
	v_mfma_i32_16x16x64_i8 v[72:75], v[168:171], v[184:187], v[72:75]
	v_mfma_i32_16x16x64_i8 v[72:75], v[172:175], v[188:191], v[72:75]
	v_mfma_i32_16x16x64_i8 v[104:107], v[176:179], v[184:187], v[104:107]
	v_mfma_i32_16x16x64_i8 v[104:107], v[180:183], v[188:191], v[104:107]
	v_mfma_i32_16x16x64_i8 v[68:71], v[168:171], v[192:195], v[68:71]
	v_mfma_i32_16x16x64_i8 v[68:71], v[172:175], v[196:199], v[68:71]
	v_mfma_i32_16x16x64_i8 v[100:103], v[176:179], v[192:195], v[100:103]
	v_mfma_i32_16x16x64_i8 v[100:103], v[180:183], v[196:199], v[100:103]
	v_mfma_i32_16x16x64_i8 v[64:67], v[168:171], v[200:203], v[64:67]
	v_mfma_i32_16x16x64_i8 v[64:67], v[172:175], v[204:207], v[64:67]
	v_mfma_i32_16x16x64_i8 v[96:99], v[176:179], v[200:203], v[96:99]
	v_mfma_i32_16x16x64_i8 v[96:99], v[180:183], v[204:207], v[96:99]
	s_setprio 2
	s_barrier
	v_mfma_i32_16x16x64_i8 v[92:95], v[168:171], v[208:211], v[92:95]
	v_mfma_i32_16x16x64_i8 v[92:95], v[172:175], v[212:215], v[92:95]
	v_mfma_i32_16x16x64_i8 v[124:127], v[176:179], v[208:211], v[124:127]
	v_mfma_i32_16x16x64_i8 v[124:127], v[180:183], v[212:215], v[124:127]
	s_setprio 0
	s_mov_b32 m0, s33
	s_add_u32 s98, s80, s8
	s_addc_u32 s99, s81, s9
	global_load_lds_dwordx4 v136, s[98:99]
	s_mov_b32 m0, s93
	s_nop 0
	s_add_u32 s98, s80, s10
	s_addc_u32 s99, s81, s11
	global_load_lds_dwordx4 v136, s[98:99]
	s_add_i32 s36, 0, 0x18000
	v_add_u32_e32 v152, s36, v153
	s_add_i32 s37, 0, 0x1c000
	ds_read_b128 v[128:131], v152
	ds_read_b128 v[132:135], v152 offset:1024
	ds_read_b128 v[146:149], v152 offset:2048
	ds_read_b128 v[164:167], v152 offset:3072
	v_add_u32_e32 v152, s37, v153
	ds_read_b128 v[168:171], v152
	ds_read_b128 v[172:175], v152 offset:1024
	ds_read_b128 v[176:179], v152 offset:2048
	ds_read_b128 v[180:183], v152 offset:3072
	ds_read_b128 v[184:187], v161 offset:32768
	ds_read_b128 v[188:191], v161 offset:33792
	ds_read_b128 v[192:195], v161 offset:34816
	ds_read_b128 v[196:199], v161 offset:35840
	ds_read_b128 v[200:203], v161 offset:36864
	ds_read_b128 v[204:207], v161 offset:37888
	ds_read_b128 v[208:211], v161 offset:38912
	ds_read_b128 v[212:215], v161 offset:39936
	s_waitcnt vmcnt(8)
	s_waitcnt lgkmcnt(0)
	s_barrier
	s_setprio 1
	s_waitcnt lgkmcnt(0)
	v_mfma_i32_16x16x64_i8 v[0:3], v[128:131], v[184:187], v[0:3]
	v_mfma_i32_16x16x64_i8 v[0:3], v[132:135], v[188:191], v[0:3]
	v_mfma_i32_16x16x64_i8 v[56:59], v[146:149], v[184:187], v[56:59]
	v_mfma_i32_16x16x64_i8 v[56:59], v[164:167], v[188:191], v[56:59]
	v_mfma_i32_16x16x64_i8 v[4:7], v[128:131], v[192:195], v[4:7]
	v_mfma_i32_16x16x64_i8 v[4:7], v[132:135], v[196:199], v[4:7]
	v_mfma_i32_16x16x64_i8 v[52:55], v[146:149], v[192:195], v[52:55]
	v_mfma_i32_16x16x64_i8 v[52:55], v[164:167], v[196:199], v[52:55]
	v_mfma_i32_16x16x64_i8 v[12:15], v[128:131], v[200:203], v[12:15]
	v_mfma_i32_16x16x64_i8 v[12:15], v[132:135], v[204:207], v[12:15]
	v_mfma_i32_16x16x64_i8 v[48:51], v[146:149], v[200:203], v[48:51]
	v_mfma_i32_16x16x64_i8 v[48:51], v[164:167], v[204:207], v[48:51]
	v_mfma_i32_16x16x64_i8 v[8:11], v[128:131], v[208:211], v[8:11]
	v_mfma_i32_16x16x64_i8 v[8:11], v[132:135], v[212:215], v[8:11]
	v_mfma_i32_16x16x64_i8 v[44:47], v[146:149], v[208:211], v[44:47]
	v_mfma_i32_16x16x64_i8 v[44:47], v[164:167], v[212:215], v[44:47]
	s_setprio 0
	s_setprio 1
	v_mfma_i32_16x16x64_i8 v[88:91], v[168:171], v[184:187], v[88:91]
	v_mfma_i32_16x16x64_i8 v[88:91], v[172:175], v[188:191], v[88:91]
	v_mfma_i32_16x16x64_i8 v[120:123], v[176:179], v[184:187], v[120:123]
	v_mfma_i32_16x16x64_i8 v[120:123], v[180:183], v[188:191], v[120:123]
	v_mfma_i32_16x16x64_i8 v[84:87], v[168:171], v[192:195], v[84:87]
	v_mfma_i32_16x16x64_i8 v[84:87], v[172:175], v[196:199], v[84:87]
	v_mfma_i32_16x16x64_i8 v[116:119], v[176:179], v[192:195], v[116:119]
	v_mfma_i32_16x16x64_i8 v[116:119], v[180:183], v[196:199], v[116:119]
	v_mfma_i32_16x16x64_i8 v[80:83], v[168:171], v[200:203], v[80:83]
	v_mfma_i32_16x16x64_i8 v[80:83], v[172:175], v[204:207], v[80:83]
	v_mfma_i32_16x16x64_i8 v[112:115], v[176:179], v[200:203], v[112:115]
	v_mfma_i32_16x16x64_i8 v[112:115], v[180:183], v[204:207], v[112:115]
	s_setprio 2
	s_barrier
	v_mfma_i32_16x16x64_i8 v[76:79], v[168:171], v[208:211], v[76:79]
	v_mfma_i32_16x16x64_i8 v[76:79], v[172:175], v[212:215], v[76:79]
	v_mfma_i32_16x16x64_i8 v[108:111], v[176:179], v[208:211], v[108:111]
	v_mfma_i32_16x16x64_i8 v[108:111], v[180:183], v[212:215], v[108:111]
	s_setprio 0
	s_add_i32 s36, s36, s63
	s_mov_b32 m0, s36
	s_add_u32 s98, vcc_lo, s46
	s_addc_u32 s99, vcc_hi, s47
	global_load_lds_dwordx4 v138, s[98:99]
	s_add_i32 m0, s36, 0x2000
	s_add_i32 s36, s37, s63
	s_add_u32 s98, vcc_lo, s48
	s_addc_u32 s99, vcc_hi, s49
	global_load_lds_dwordx4 v138, s[98:99]
	s_mov_b32 m0, s36
	s_add_u32 s98, vcc_lo, s54
	s_addc_u32 s99, vcc_hi, s55
	global_load_lds_dwordx4 v138, s[98:99]
	s_add_i32 m0, s36, 0x2000
	s_nop 0
	s_add_u32 s98, vcc_lo, s56
	s_addc_u32 s99, vcc_hi, s57
	global_load_lds_dwordx4 v138, s[98:99]
	s_mov_b32 m0, s95
	s_nop 0
	s_add_u32 s98, s80, s46
	s_addc_u32 s99, s81, s47
	global_load_lds_dwordx4 v136, s[98:99]
	s_mov_b32 m0, s82
	s_nop 0
	s_add_u32 s98, s80, s48
	s_addc_u32 s99, s81, s49
	global_load_lds_dwordx4 v136, s[98:99]
	ds_read_b128 v[184:187], v161 offset:49152
	ds_read_b128 v[188:191], v161 offset:50176
	ds_read_b128 v[192:195], v161 offset:51200
	ds_read_b128 v[196:199], v161 offset:52224
	ds_read_b128 v[200:203], v161 offset:53248
	ds_read_b128 v[204:207], v161 offset:54272
	ds_read_b128 v[208:211], v161 offset:55296
	ds_read_b128 v[212:215], v161 offset:56320
	s_waitcnt vmcnt(8)
	s_waitcnt lgkmcnt(0)
	s_barrier
	s_setprio 1
	s_waitcnt lgkmcnt(0)
	v_mfma_i32_16x16x64_i8 v[20:23], v[128:131], v[184:187], v[20:23]
	v_mfma_i32_16x16x64_i8 v[20:23], v[132:135], v[188:191], v[20:23]
	v_mfma_i32_16x16x64_i8 v[40:43], v[146:149], v[184:187], v[40:43]
	v_mfma_i32_16x16x64_i8 v[40:43], v[164:167], v[188:191], v[40:43]
	v_mfma_i32_16x16x64_i8 v[16:19], v[128:131], v[192:195], v[16:19]
	v_mfma_i32_16x16x64_i8 v[16:19], v[132:135], v[196:199], v[16:19]
	v_mfma_i32_16x16x64_i8 v[36:39], v[146:149], v[192:195], v[36:39]
	v_mfma_i32_16x16x64_i8 v[36:39], v[164:167], v[196:199], v[36:39]
	v_mfma_i32_16x16x64_i8 v[24:27], v[128:131], v[200:203], v[24:27]
	v_mfma_i32_16x16x64_i8 v[24:27], v[132:135], v[204:207], v[24:27]
	v_mfma_i32_16x16x64_i8 v[32:35], v[146:149], v[200:203], v[32:35]
	v_mfma_i32_16x16x64_i8 v[32:35], v[164:167], v[204:207], v[32:35]
	v_mfma_i32_16x16x64_i8 v[28:31], v[128:131], v[208:211], v[28:31]
	v_mfma_i32_16x16x64_i8 v[28:31], v[132:135], v[212:215], v[28:31]
	v_mfma_i32_16x16x64_i8 v[60:63], v[146:149], v[208:211], v[60:63]
	v_mfma_i32_16x16x64_i8 v[60:63], v[164:167], v[212:215], v[60:63]
	s_setprio 0
	s_setprio 1
	v_mfma_i32_16x16x64_i8 v[72:75], v[168:171], v[184:187], v[72:75]
	v_mfma_i32_16x16x64_i8 v[72:75], v[172:175], v[188:191], v[72:75]
	v_mfma_i32_16x16x64_i8 v[104:107], v[176:179], v[184:187], v[104:107]
	v_mfma_i32_16x16x64_i8 v[104:107], v[180:183], v[188:191], v[104:107]
	v_mfma_i32_16x16x64_i8 v[68:71], v[168:171], v[192:195], v[68:71]
	v_mfma_i32_16x16x64_i8 v[68:71], v[172:175], v[196:199], v[68:71]
	v_mfma_i32_16x16x64_i8 v[100:103], v[176:179], v[192:195], v[100:103]
	v_mfma_i32_16x16x64_i8 v[100:103], v[180:183], v[196:199], v[100:103]
	v_mfma_i32_16x16x64_i8 v[64:67], v[168:171], v[200:203], v[64:67]
	v_mfma_i32_16x16x64_i8 v[64:67], v[172:175], v[204:207], v[64:67]
	v_mfma_i32_16x16x64_i8 v[96:99], v[176:179], v[200:203], v[96:99]
	v_mfma_i32_16x16x64_i8 v[96:99], v[180:183], v[204:207], v[96:99]
	s_setprio 2
	s_barrier
	v_mfma_i32_16x16x64_i8 v[92:95], v[168:171], v[208:211], v[92:95]
	v_mfma_i32_16x16x64_i8 v[92:95], v[172:175], v[212:215], v[92:95]
	v_mfma_i32_16x16x64_i8 v[124:127], v[176:179], v[208:211], v[124:127]
	v_mfma_i32_16x16x64_i8 v[124:127], v[180:183], v[212:215], v[124:127]
	s_setprio 0
	s_add_i32 s78, s78, 2
	s_add_u32 s24, s24, 0x100
	s_addc_u32 s45, s45, 0
	s_add_u32 s22, s22, 0x100
	s_addc_u32 s23, s23, 0
	s_cmp_gt_u32 s78, 29
	s_cbranch_scc0 .LBB0_225
	v_readlane_b32 s14, v250, 9
	v_readlane_b32 s15, v250, 10
	s_and_b64 vcc, exec, s[14:15]
	s_cbranch_vccz .LBB0_228
	s_barrier

.LBB0_298:
	s_add_u32 s36, s78, 0xfff00080
	s_addc_u32 s37, s79, -1
	s_cmp_eq_u32 s81, 60
	s_cselect_b32 s97, s5, s37
	s_cselect_b32 s96, s14, s36
	s_cselect_b32 vcc_hi, s20, s80
	s_cselect_b32 vcc_lo, s21, s22
	s_add_i32 m0, s33, 0xc000
	s_nop 0
	global_load_lds_dwordx4 v140, s[78:79]
	s_add_i32 m0, s33, 0xe000
	s_nop 0
	s_add_u32 s98, s78, s0
	s_addc_u32 s99, s79, s1
	global_load_lds_dwordx4 v140, s[98:99]
	ds_read_b128 v[128:131], v153
	ds_read_b128 v[132:135], v153 offset:1024
	ds_read_b128 v[146:149], v153 offset:2048
	ds_read_b128 v[158:161], v153 offset:3072
	ds_read_b128 v[162:165], v154
	ds_read_b128 v[166:169], v154 offset:1024
	ds_read_b128 v[170:173], v154 offset:2048
	ds_read_b128 v[174:177], v154 offset:3072
	ds_read_b128 v[178:181], v155
	ds_read_b128 v[182:185], v155 offset:1024
	ds_read_b128 v[186:189], v155 offset:2048
	ds_read_b128 v[190:193], v155 offset:3072
	ds_read_b128 v[194:197], v155 offset:4096
	ds_read_b128 v[198:201], v155 offset:5120
	ds_read_b128 v[202:205], v155 offset:6144
	ds_read_b128 v[206:209], v155 offset:7168
	s_waitcnt vmcnt(8)
	s_waitcnt lgkmcnt(0)
	s_barrier
	s_setprio 1
	s_waitcnt lgkmcnt(0)
	v_mfma_f32_16x16x32_bf16 v[124:127], v[128:131], v[178:181], v[124:127]
	v_mfma_f32_16x16x32_bf16 v[124:127], v[132:135], v[182:185], v[124:127]
	v_mfma_f32_16x16x32_bf16 v[120:123], v[146:149], v[178:181], v[120:123]
	v_mfma_f32_16x16x32_bf16 v[120:123], v[158:161], v[182:185], v[120:123]
	v_mfma_f32_16x16x32_bf16 v[112:115], v[128:131], v[186:189], v[112:115]
	v_mfma_f32_16x16x32_bf16 v[112:115], v[132:135], v[190:193], v[112:115]
	v_mfma_f32_16x16x32_bf16 v[108:111], v[146:149], v[186:189], v[108:111]
	v_mfma_f32_16x16x32_bf16 v[108:111], v[158:161], v[190:193], v[108:111]
	v_mfma_f32_16x16x32_bf16 v[100:103], v[128:131], v[194:197], v[100:103]
	v_mfma_f32_16x16x32_bf16 v[100:103], v[132:135], v[198:201], v[100:103]
	v_mfma_f32_16x16x32_bf16 v[92:95], v[146:149], v[194:197], v[92:95]
	v_mfma_f32_16x16x32_bf16 v[92:95], v[158:161], v[198:201], v[92:95]
	v_mfma_f32_16x16x32_bf16 v[84:87], v[128:131], v[202:205], v[84:87]
	v_mfma_f32_16x16x32_bf16 v[84:87], v[132:135], v[206:209], v[84:87]
	v_mfma_f32_16x16x32_bf16 v[76:79], v[146:149], v[202:205], v[76:79]
	v_mfma_f32_16x16x32_bf16 v[76:79], v[158:161], v[206:209], v[76:79]
	s_setprio 0
	s_setprio 1
	v_mfma_f32_16x16x32_bf16 v[116:119], v[162:165], v[178:181], v[116:119]
	v_mfma_f32_16x16x32_bf16 v[116:119], v[166:169], v[182:185], v[116:119]
	v_mfma_f32_16x16x32_bf16 v[104:107], v[170:173], v[178:181], v[104:107]
	v_mfma_f32_16x16x32_bf16 v[104:107], v[174:177], v[182:185], v[104:107]
	v_mfma_f32_16x16x32_bf16 v[96:99], v[162:165], v[186:189], v[96:99]
	v_mfma_f32_16x16x32_bf16 v[96:99], v[166:169], v[190:193], v[96:99]
	v_mfma_f32_16x16x32_bf16 v[88:91], v[170:173], v[186:189], v[88:91]
	v_mfma_f32_16x16x32_bf16 v[88:91], v[174:177], v[190:193], v[88:91]
	v_mfma_f32_16x16x32_bf16 v[80:83], v[162:165], v[194:197], v[80:83]
	v_mfma_f32_16x16x32_bf16 v[80:83], v[166:169], v[198:201], v[80:83]
	v_mfma_f32_16x16x32_bf16 v[72:75], v[170:173], v[194:197], v[72:75]
	v_mfma_f32_16x16x32_bf16 v[72:75], v[174:177], v[198:201], v[72:75]
	s_setprio 2
	s_barrier
	v_mfma_f32_16x16x32_bf16 v[68:71], v[162:165], v[202:205], v[68:71]
	v_mfma_f32_16x16x32_bf16 v[68:71], v[166:169], v[206:209], v[68:71]
	v_mfma_f32_16x16x32_bf16 v[64:67], v[170:173], v[202:205], v[64:67]
	v_mfma_f32_16x16x32_bf16 v[64:67], v[174:177], v[206:209], v[64:67]
	s_setprio 0
	s_add_i32 s36, s82, s63
	s_mov_b32 m0, s36
	s_nop 0
	global_load_lds_dwordx4 v138, vcc
	s_add_i32 m0, s36, 0x2000
	s_add_i32 s36, s83, s63
	s_add_u32 s98, vcc_lo, s0
	s_addc_u32 s99, vcc_hi, s1
	global_load_lds_dwordx4 v138, s[98:99]
	s_mov_b32 m0, s36
	s_nop 0
	s_add_u32 s98, vcc_lo, s6
	s_addc_u32 s99, vcc_hi, s7
	global_load_lds_dwordx4 v138, s[98:99]
	s_add_i32 m0, s36, 0x2000
	s_nop 0
	s_add_u32 s98, vcc_lo, s8
	s_addc_u32 s99, vcc_hi, s9
	global_load_lds_dwordx4 v138, s[98:99]
	s_mov_b32 m0, s33
	s_nop 0
	global_load_lds_dwordx4 v136, s[96:97]
	s_mov_b32 m0, s55
	s_nop 0
	s_add_u32 s98, s96, s0
	s_addc_u32 s99, s97, s1
	global_load_lds_dwordx4 v136, s[98:99]
	ds_read_b128 v[178:181], v155 offset:16384
	ds_read_b128 v[182:185], v155 offset:17408
	ds_read_b128 v[186:189], v155 offset:18432
	ds_read_b128 v[190:193], v155 offset:19456
	ds_read_b128 v[194:197], v155 offset:20480
	ds_read_b128 v[198:201], v155 offset:21504
	ds_read_b128 v[202:205], v155 offset:22528
	ds_read_b128 v[206:209], v155 offset:23552
	s_waitcnt vmcnt(8)
	s_waitcnt lgkmcnt(0)
	s_barrier
	s_setprio 1
	s_waitcnt lgkmcnt(0)
	v_mfma_f32_16x16x32_bf16 v[60:63], v[128:131], v[178:181], v[60:63]
	v_mfma_f32_16x16x32_bf16 v[60:63], v[132:135], v[182:185], v[60:63]
	v_mfma_f32_16x16x32_bf16 v[56:59], v[146:149], v[178:181], v[56:59]
	v_mfma_f32_16x16x32_bf16 v[56:59], v[158:161], v[182:185], v[56:59]
	v_mfma_f32_16x16x32_bf16 v[52:55], v[128:131], v[186:189], v[52:55]
	v_mfma_f32_16x16x32_bf16 v[52:55], v[132:135], v[190:193], v[52:55]
	v_mfma_f32_16x16x32_bf16 v[44:47], v[146:149], v[186:189], v[44:47]
	v_mfma_f32_16x16x32_bf16 v[44:47], v[158:161], v[190:193], v[44:47]
	v_mfma_f32_16x16x32_bf16 v[36:39], v[128:131], v[194:197], v[36:39]
	v_mfma_f32_16x16x32_bf16 v[36:39], v[132:135], v[198:201], v[36:39]
	v_mfma_f32_16x16x32_bf16 v[28:31], v[146:149], v[194:197], v[28:31]
	v_mfma_f32_16x16x32_bf16 v[28:31], v[158:161], v[198:201], v[28:31]
	v_mfma_f32_16x16x32_bf16 v[20:23], v[128:131], v[202:205], v[20:23]
	v_mfma_f32_16x16x32_bf16 v[20:23], v[132:135], v[206:209], v[20:23]
	v_mfma_f32_16x16x32_bf16 v[12:15], v[146:149], v[202:205], v[12:15]
	v_mfma_f32_16x16x32_bf16 v[12:15], v[158:161], v[206:209], v[12:15]
	s_setprio 0
	s_setprio 1
	v_mfma_f32_16x16x32_bf16 v[48:51], v[162:165], v[178:181], v[48:51]
	v_mfma_f32_16x16x32_bf16 v[48:51], v[166:169], v[182:185], v[48:51]
	v_mfma_f32_16x16x32_bf16 v[40:43], v[170:173], v[178:181], v[40:43]
	v_mfma_f32_16x16x32_bf16 v[40:43], v[174:177], v[182:185], v[40:43]
	v_mfma_f32_16x16x32_bf16 v[32:35], v[162:165], v[186:189], v[32:35]
	v_mfma_f32_16x16x32_bf16 v[32:35], v[166:169], v[190:193], v[32:35]
	v_mfma_f32_16x16x32_bf16 v[24:27], v[170:173], v[186:189], v[24:27]
	v_mfma_f32_16x16x32_bf16 v[24:27], v[174:177], v[190:193], v[24:27]
	v_mfma_f32_16x16x32_bf16 v[16:19], v[162:165], v[194:197], v[16:19]
	v_mfma_f32_16x16x32_bf16 v[16:19], v[166:169], v[198:201], v[16:19]
	v_mfma_f32_16x16x32_bf16 v[8:11], v[170:173], v[194:197], v[8:11]
	v_mfma_f32_16x16x32_bf16 v[8:11], v[174:177], v[198:201], v[8:11]
	s_setprio 2
	s_barrier
	v_mfma_f32_16x16x32_bf16 v[4:7], v[162:165], v[202:205], v[4:7]
	v_mfma_f32_16x16x32_bf16 v[4:7], v[166:169], v[206:209], v[4:7]
	v_mfma_f32_16x16x32_bf16 v[0:3], v[170:173], v[202:205], v[0:3]
	v_mfma_f32_16x16x32_bf16 v[0:3], v[174:177], v[206:209], v[0:3]
	s_setprio 0
	s_mov_b32 m0, s57
	s_add_u32 s98, s96, s6
	s_addc_u32 s99, s97, s7
	global_load_lds_dwordx4 v136, s[98:99]
	s_mov_b32 m0, s59
	s_nop 0
	s_add_u32 s98, s96, s8
	s_addc_u32 s99, s97, s9
	global_load_lds_dwordx4 v136, s[98:99]
	s_add_i32 s36, 0, 0x18000
	v_add_u32_e32 v157, s36, v152
	s_add_i32 s37, 0, 0x1c000
	ds_read_b128 v[128:131], v157
	ds_read_b128 v[132:135], v157 offset:1024
	ds_read_b128 v[146:149], v157 offset:2048
	ds_read_b128 v[158:161], v157 offset:3072
	v_add_u32_e32 v157, s37, v152
	ds_read_b128 v[162:165], v157
	ds_read_b128 v[166:169], v157 offset:1024
	ds_read_b128 v[170:173], v157 offset:2048
	ds_read_b128 v[174:177], v157 offset:3072
	ds_read_b128 v[178:181], v155 offset:32768
	ds_read_b128 v[182:185], v155 offset:33792
	ds_read_b128 v[186:189], v155 offset:34816
	ds_read_b128 v[190:193], v155 offset:35840
	ds_read_b128 v[194:197], v155 offset:36864
	ds_read_b128 v[198:201], v155 offset:37888
	ds_read_b128 v[202:205], v155 offset:38912
	ds_read_b128 v[206:209], v155 offset:39936
	s_waitcnt vmcnt(8)
	s_waitcnt lgkmcnt(0)
	s_barrier
	s_setprio 1
	s_waitcnt lgkmcnt(0)
	v_mfma_f32_16x16x32_bf16 v[124:127], v[128:131], v[178:181], v[124:127]
	v_mfma_f32_16x16x32_bf16 v[124:127], v[132:135], v[182:185], v[124:127]
	v_mfma_f32_16x16x32_bf16 v[120:123], v[146:149], v[178:181], v[120:123]
	v_mfma_f32_16x16x32_bf16 v[120:123], v[158:161], v[182:185], v[120:123]
	v_mfma_f32_16x16x32_bf16 v[112:115], v[128:131], v[186:189], v[112:115]
	v_mfma_f32_16x16x32_bf16 v[112:115], v[132:135], v[190:193], v[112:115]
	v_mfma_f32_16x16x32_bf16 v[108:111], v[146:149], v[186:189], v[108:111]
	v_mfma_f32_16x16x32_bf16 v[108:111], v[158:161], v[190:193], v[108:111]
	v_mfma_f32_16x16x32_bf16 v[100:103], v[128:131], v[194:197], v[100:103]
	v_mfma_f32_16x16x32_bf16 v[100:103], v[132:135], v[198:201], v[100:103]
	v_mfma_f32_16x16x32_bf16 v[92:95], v[146:149], v[194:197], v[92:95]
	v_mfma_f32_16x16x32_bf16 v[92:95], v[158:161], v[198:201], v[92:95]
	v_mfma_f32_16x16x32_bf16 v[84:87], v[128:131], v[202:205], v[84:87]
	v_mfma_f32_16x16x32_bf16 v[84:87], v[132:135], v[206:209], v[84:87]
	v_mfma_f32_16x16x32_bf16 v[76:79], v[146:149], v[202:205], v[76:79]
	v_mfma_f32_16x16x32_bf16 v[76:79], v[158:161], v[206:209], v[76:79]
	s_setprio 0
	s_setprio 1
	v_mfma_f32_16x16x32_bf16 v[116:119], v[162:165], v[178:181], v[116:119]
	v_mfma_f32_16x16x32_bf16 v[116:119], v[166:169], v[182:185], v[116:119]
	v_mfma_f32_16x16x32_bf16 v[104:107], v[170:173], v[178:181], v[104:107]
	v_mfma_f32_16x16x32_bf16 v[104:107], v[174:177], v[182:185], v[104:107]
	v_mfma_f32_16x16x32_bf16 v[96:99], v[162:165], v[186:189], v[96:99]
	v_mfma_f32_16x16x32_bf16 v[96:99], v[166:169], v[190:193], v[96:99]
	v_mfma_f32_16x16x32_bf16 v[88:91], v[170:173], v[186:189], v[88:91]
	v_mfma_f32_16x16x32_bf16 v[88:91], v[174:177], v[190:193], v[88:91]
	v_mfma_f32_16x16x32_bf16 v[80:83], v[162:165], v[194:197], v[80:83]
	v_mfma_f32_16x16x32_bf16 v[80:83], v[166:169], v[198:201], v[80:83]
	v_mfma_f32_16x16x32_bf16 v[72:75], v[170:173], v[194:197], v[72:75]
	v_mfma_f32_16x16x32_bf16 v[72:75], v[174:177], v[198:201], v[72:75]
	s_setprio 2
	s_barrier
	v_mfma_f32_16x16x32_bf16 v[68:71], v[162:165], v[202:205], v[68:71]
	v_mfma_f32_16x16x32_bf16 v[68:71], v[166:169], v[206:209], v[68:71]
	v_mfma_f32_16x16x32_bf16 v[64:67], v[170:173], v[202:205], v[64:67]
	v_mfma_f32_16x16x32_bf16 v[64:67], v[174:177], v[206:209], v[64:67]
	s_setprio 0
	s_add_i32 s36, s36, s63
	s_mov_b32 m0, s36
	s_add_u32 s98, vcc_lo, s24
	s_addc_u32 s99, vcc_hi, s25
	global_load_lds_dwordx4 v138, s[98:99]
	s_add_i32 m0, s36, 0x2000
	s_add_i32 s36, s37, s63
	s_add_u32 s98, vcc_lo, s34
	s_addc_u32 s99, vcc_hi, s35
	global_load_lds_dwordx4 v138, s[98:99]
	s_mov_b32 m0, s36
	s_add_u32 s98, vcc_lo, s12
	s_addc_u32 s99, vcc_hi, s13
	global_load_lds_dwordx4 v138, s[98:99]
	s_add_i32 m0, s36, 0x2000
	s_nop 0
	s_add_u32 s98, vcc_lo, s18
	s_addc_u32 s99, vcc_hi, s19
	global_load_lds_dwordx4 v138, s[98:99]
	s_mov_b32 m0, s68
	s_nop 0
	s_add_u32 s98, s96, s24
	s_addc_u32 s99, s97, s25
	global_load_lds_dwordx4 v136, s[98:99]
	s_mov_b32 m0, s69
	s_nop 0
	s_add_u32 s98, s96, s34
	s_addc_u32 s99, s97, s35
	global_load_lds_dwordx4 v136, s[98:99]
	ds_read_b128 v[178:181], v155 offset:49152
	ds_read_b128 v[182:185], v155 offset:50176
	ds_read_b128 v[186:189], v155 offset:51200
	ds_read_b128 v[190:193], v155 offset:52224
	ds_read_b128 v[194:197], v155 offset:53248
	ds_read_b128 v[198:201], v155 offset:54272
	ds_read_b128 v[202:205], v155 offset:55296
	ds_read_b128 v[206:209], v155 offset:56320
	s_waitcnt vmcnt(8)
	s_waitcnt lgkmcnt(0)
	s_barrier
	s_setprio 1
	s_waitcnt lgkmcnt(0)
	v_mfma_f32_16x16x32_bf16 v[60:63], v[128:131], v[178:181], v[60:63]
	v_mfma_f32_16x16x32_bf16 v[60:63], v[132:135], v[182:185], v[60:63]
	v_mfma_f32_16x16x32_bf16 v[56:59], v[146:149], v[178:181], v[56:59]
	v_mfma_f32_16x16x32_bf16 v[56:59], v[158:161], v[182:185], v[56:59]
	v_mfma_f32_16x16x32_bf16 v[52:55], v[128:131], v[186:189], v[52:55]
	v_mfma_f32_16x16x32_bf16 v[52:55], v[132:135], v[190:193], v[52:55]
	v_mfma_f32_16x16x32_bf16 v[44:47], v[146:149], v[186:189], v[44:47]
	v_mfma_f32_16x16x32_bf16 v[44:47], v[158:161], v[190:193], v[44:47]
	v_mfma_f32_16x16x32_bf16 v[36:39], v[128:131], v[194:197], v[36:39]
	v_mfma_f32_16x16x32_bf16 v[36:39], v[132:135], v[198:201], v[36:39]
	v_mfma_f32_16x16x32_bf16 v[28:31], v[146:149], v[194:197], v[28:31]
	v_mfma_f32_16x16x32_bf16 v[28:31], v[158:161], v[198:201], v[28:31]
	v_mfma_f32_16x16x32_bf16 v[20:23], v[128:131], v[202:205], v[20:23]
	v_mfma_f32_16x16x32_bf16 v[20:23], v[132:135], v[206:209], v[20:23]
	v_mfma_f32_16x16x32_bf16 v[12:15], v[146:149], v[202:205], v[12:15]
	v_mfma_f32_16x16x32_bf16 v[12:15], v[158:161], v[206:209], v[12:15]
	s_setprio 0
	s_setprio 1
	v_mfma_f32_16x16x32_bf16 v[48:51], v[162:165], v[178:181], v[48:51]
	v_mfma_f32_16x16x32_bf16 v[48:51], v[166:169], v[182:185], v[48:51]
	v_mfma_f32_16x16x32_bf16 v[40:43], v[170:173], v[178:181], v[40:43]
	v_mfma_f32_16x16x32_bf16 v[40:43], v[174:177], v[182:185], v[40:43]
	v_mfma_f32_16x16x32_bf16 v[32:35], v[162:165], v[186:189], v[32:35]
	v_mfma_f32_16x16x32_bf16 v[32:35], v[166:169], v[190:193], v[32:35]
	v_mfma_f32_16x16x32_bf16 v[24:27], v[170:173], v[186:189], v[24:27]
	v_mfma_f32_16x16x32_bf16 v[24:27], v[174:177], v[190:193], v[24:27]
	v_mfma_f32_16x16x32_bf16 v[16:19], v[162:165], v[194:197], v[16:19]
	v_mfma_f32_16x16x32_bf16 v[16:19], v[166:169], v[198:201], v[16:19]
	v_mfma_f32_16x16x32_bf16 v[8:11], v[170:173], v[194:197], v[8:11]
	v_mfma_f32_16x16x32_bf16 v[8:11], v[174:177], v[198:201], v[8:11]
	s_setprio 2
	s_barrier
	v_mfma_f32_16x16x32_bf16 v[4:7], v[162:165], v[202:205], v[4:7]
	v_mfma_f32_16x16x32_bf16 v[4:7], v[166:169], v[206:209], v[4:7]
	v_mfma_f32_16x16x32_bf16 v[0:3], v[170:173], v[202:205], v[0:3]
	v_mfma_f32_16x16x32_bf16 v[0:3], v[174:177], v[206:209], v[0:3]
	s_setprio 0
	s_add_i32 s81, s81, 2
	s_add_u32 s22, s22, 0x100
	s_addc_u32 s80, s80, 0
	s_add_u32 s78, s78, 0x100
	s_addc_u32 s79, s79, 0
	s_cmp_gt_u32 s81, 61
	s_cbranch_scc0 .LBB0_298
	s_and_b64 vcc, exec, s[26:27]
	s_cbranch_vccz .LBB0_301
	s_barrier

.LBB0_627:
	s_add_u32 s50, s60, 0xfff00080
	s_addc_u32 s51, s61, -1
	s_cmp_eq_u32 s62, 60
	s_cselect_b32 s77, s5, s51
	s_cselect_b32 s76, s49, s50
	s_cselect_b32 s79, s47, s75
	s_cselect_b32 s78, s59, s74
	s_add_i32 m0, s20, 0xc000
	s_nop 0
	global_load_lds_dwordx4 v136, s[60:61]
	s_add_i32 m0, s20, 0xe000
	s_nop 0
	s_add_u32 s98, s60, s6
	s_addc_u32 s99, s61, s7
	global_load_lds_dwordx4 v136, s[98:99]
	ds_read_b128 v[128:131], v151
	ds_read_b128 v[142:145], v151 offset:1024
	ds_read_b128 v[146:149], v151 offset:2048
	ds_read_b128 v[154:157], v151 offset:3072
	ds_read_b128 v[158:161], v152
	ds_read_b128 v[162:165], v152 offset:1024
	ds_read_b128 v[166:169], v152 offset:2048
	ds_read_b128 v[170:173], v152 offset:3072
	ds_read_b128 v[174:177], v153
	ds_read_b128 v[178:181], v153 offset:1024
	ds_read_b128 v[182:185], v153 offset:2048
	ds_read_b128 v[186:189], v153 offset:3072
	ds_read_b128 v[190:193], v153 offset:4096
	ds_read_b128 v[194:197], v153 offset:5120
	ds_read_b128 v[198:201], v153 offset:6144
	ds_read_b128 v[202:205], v153 offset:7168
	s_waitcnt vmcnt(8)
	s_waitcnt lgkmcnt(0)
	s_barrier
	s_setprio 1
	s_waitcnt lgkmcnt(0)
	v_mfma_f32_16x16x32_bf16 v[124:127], v[128:131], v[174:177], v[124:127]
	v_mfma_f32_16x16x32_bf16 v[124:127], v[142:145], v[178:181], v[124:127]
	v_mfma_f32_16x16x32_bf16 v[120:123], v[146:149], v[174:177], v[120:123]
	v_mfma_f32_16x16x32_bf16 v[120:123], v[154:157], v[178:181], v[120:123]
	v_mfma_f32_16x16x32_bf16 v[116:119], v[128:131], v[182:185], v[116:119]
	v_mfma_f32_16x16x32_bf16 v[116:119], v[142:145], v[186:189], v[116:119]
	v_mfma_f32_16x16x32_bf16 v[112:115], v[146:149], v[182:185], v[112:115]
	v_mfma_f32_16x16x32_bf16 v[112:115], v[154:157], v[186:189], v[112:115]
	v_mfma_f32_16x16x32_bf16 v[108:111], v[128:131], v[190:193], v[108:111]
	v_mfma_f32_16x16x32_bf16 v[108:111], v[142:145], v[194:197], v[108:111]
	v_mfma_f32_16x16x32_bf16 v[104:107], v[146:149], v[190:193], v[104:107]
	v_mfma_f32_16x16x32_bf16 v[104:107], v[154:157], v[194:197], v[104:107]
	v_mfma_f32_16x16x32_bf16 v[100:103], v[128:131], v[198:201], v[100:103]
	v_mfma_f32_16x16x32_bf16 v[100:103], v[142:145], v[202:205], v[100:103]
	v_mfma_f32_16x16x32_bf16 v[96:99], v[146:149], v[198:201], v[96:99]
	v_mfma_f32_16x16x32_bf16 v[96:99], v[154:157], v[202:205], v[96:99]
	s_setprio 0
	s_setprio 1
	v_mfma_f32_16x16x32_bf16 v[92:95], v[158:161], v[174:177], v[92:95]
	v_mfma_f32_16x16x32_bf16 v[92:95], v[162:165], v[178:181], v[92:95]
	v_mfma_f32_16x16x32_bf16 v[88:91], v[166:169], v[174:177], v[88:91]
	v_mfma_f32_16x16x32_bf16 v[88:91], v[170:173], v[178:181], v[88:91]
	v_mfma_f32_16x16x32_bf16 v[84:87], v[158:161], v[182:185], v[84:87]
	v_mfma_f32_16x16x32_bf16 v[84:87], v[162:165], v[186:189], v[84:87]
	v_mfma_f32_16x16x32_bf16 v[80:83], v[166:169], v[182:185], v[80:83]
	v_mfma_f32_16x16x32_bf16 v[80:83], v[170:173], v[186:189], v[80:83]
	v_mfma_f32_16x16x32_bf16 v[76:79], v[158:161], v[190:193], v[76:79]
	v_mfma_f32_16x16x32_bf16 v[76:79], v[162:165], v[194:197], v[76:79]
	v_mfma_f32_16x16x32_bf16 v[72:75], v[166:169], v[190:193], v[72:75]
	v_mfma_f32_16x16x32_bf16 v[72:75], v[170:173], v[194:197], v[72:75]
	s_setprio 2
	s_barrier
	v_mfma_f32_16x16x32_bf16 v[68:71], v[158:161], v[198:201], v[68:71]
	v_mfma_f32_16x16x32_bf16 v[68:71], v[162:165], v[202:205], v[68:71]
	v_mfma_f32_16x16x32_bf16 v[64:67], v[166:169], v[198:201], v[64:67]
	v_mfma_f32_16x16x32_bf16 v[64:67], v[170:173], v[202:205], v[64:67]
	s_setprio 0
	s_add_i32 s50, s72, s14
	s_mov_b32 m0, s50
	s_nop 0
	global_load_lds_dwordx4 v134, s[78:79]
	s_add_i32 m0, s50, 0x2000
	s_add_i32 s50, s73, s14
	s_add_u32 s98, s78, s6
	s_addc_u32 s99, s79, s7
	global_load_lds_dwordx4 v134, s[98:99]
	s_mov_b32 m0, s50
	s_nop 0
	s_add_u32 s98, s78, s8
	s_addc_u32 s99, s79, s9
	global_load_lds_dwordx4 v134, s[98:99]
	s_add_i32 m0, s50, 0x2000
	s_nop 0
	s_add_u32 s98, s78, s10
	s_addc_u32 s99, s79, s11
	global_load_lds_dwordx4 v134, s[98:99]
	s_mov_b32 m0, s20
	s_nop 0
	global_load_lds_dwordx4 v132, s[76:77]
	s_mov_b32 m0, s21
	s_nop 0
	s_add_u32 s98, s76, s6
	s_addc_u32 s99, s77, s7
	global_load_lds_dwordx4 v132, s[98:99]
	ds_read_b128 v[174:177], v153 offset:16384
	ds_read_b128 v[178:181], v153 offset:17408
	ds_read_b128 v[182:185], v153 offset:18432
	ds_read_b128 v[186:189], v153 offset:19456
	ds_read_b128 v[190:193], v153 offset:20480
	ds_read_b128 v[194:197], v153 offset:21504
	ds_read_b128 v[198:201], v153 offset:22528
	ds_read_b128 v[202:205], v153 offset:23552
	s_waitcnt vmcnt(8)
	s_waitcnt lgkmcnt(0)
	s_barrier
	s_setprio 1
	s_waitcnt lgkmcnt(0)
	v_mfma_f32_16x16x32_bf16 v[60:63], v[128:131], v[174:177], v[60:63]
	v_mfma_f32_16x16x32_bf16 v[60:63], v[142:145], v[178:181], v[60:63]
	v_mfma_f32_16x16x32_bf16 v[56:59], v[146:149], v[174:177], v[56:59]
	v_mfma_f32_16x16x32_bf16 v[56:59], v[154:157], v[178:181], v[56:59]
	v_mfma_f32_16x16x32_bf16 v[52:55], v[128:131], v[182:185], v[52:55]
	v_mfma_f32_16x16x32_bf16 v[52:55], v[142:145], v[186:189], v[52:55]
	v_mfma_f32_16x16x32_bf16 v[48:51], v[146:149], v[182:185], v[48:51]
	v_mfma_f32_16x16x32_bf16 v[48:51], v[154:157], v[186:189], v[48:51]
	v_mfma_f32_16x16x32_bf16 v[44:47], v[128:131], v[190:193], v[44:47]
	v_mfma_f32_16x16x32_bf16 v[44:47], v[142:145], v[194:197], v[44:47]
	v_mfma_f32_16x16x32_bf16 v[40:43], v[146:149], v[190:193], v[40:43]
	v_mfma_f32_16x16x32_bf16 v[40:43], v[154:157], v[194:197], v[40:43]
	v_mfma_f32_16x16x32_bf16 v[36:39], v[128:131], v[198:201], v[36:39]
	v_mfma_f32_16x16x32_bf16 v[36:39], v[142:145], v[202:205], v[36:39]
	v_mfma_f32_16x16x32_bf16 v[32:35], v[146:149], v[198:201], v[32:35]
	v_mfma_f32_16x16x32_bf16 v[32:35], v[154:157], v[202:205], v[32:35]
	s_setprio 0
	s_setprio 1
	v_mfma_f32_16x16x32_bf16 v[28:31], v[158:161], v[174:177], v[28:31]
	v_mfma_f32_16x16x32_bf16 v[28:31], v[162:165], v[178:181], v[28:31]
	v_mfma_f32_16x16x32_bf16 v[24:27], v[166:169], v[174:177], v[24:27]
	v_mfma_f32_16x16x32_bf16 v[24:27], v[170:173], v[178:181], v[24:27]
	v_mfma_f32_16x16x32_bf16 v[20:23], v[158:161], v[182:185], v[20:23]
	v_mfma_f32_16x16x32_bf16 v[20:23], v[162:165], v[186:189], v[20:23]
	v_mfma_f32_16x16x32_bf16 v[16:19], v[166:169], v[182:185], v[16:19]
	v_mfma_f32_16x16x32_bf16 v[16:19], v[170:173], v[186:189], v[16:19]
	v_mfma_f32_16x16x32_bf16 v[12:15], v[158:161], v[190:193], v[12:15]
	v_mfma_f32_16x16x32_bf16 v[12:15], v[162:165], v[194:197], v[12:15]
	v_mfma_f32_16x16x32_bf16 v[8:11], v[166:169], v[190:193], v[8:11]
	v_mfma_f32_16x16x32_bf16 v[8:11], v[170:173], v[194:197], v[8:11]
	s_setprio 2
	s_barrier
	v_mfma_f32_16x16x32_bf16 v[4:7], v[158:161], v[198:201], v[4:7]
	v_mfma_f32_16x16x32_bf16 v[4:7], v[162:165], v[202:205], v[4:7]
	v_mfma_f32_16x16x32_bf16 v[0:3], v[166:169], v[198:201], v[0:3]
	v_mfma_f32_16x16x32_bf16 v[0:3], v[170:173], v[202:205], v[0:3]
	s_setprio 0
	s_mov_b32 m0, s33
	s_add_u32 s98, s76, s8
	s_addc_u32 s99, s77, s9
	global_load_lds_dwordx4 v132, s[98:99]
	s_mov_b32 m0, s64
	s_nop 0
	s_add_u32 s98, s76, s10
	s_addc_u32 s99, s77, s11
	global_load_lds_dwordx4 v132, s[98:99]
	s_add_i32 s50, 0, 0x18000
	s_add_i32 s51, 0, 0x1c000
	v_add_u32_e32 v154, s50, v150
	v_add_u32_e32 v170, s51, v150
	ds_read_b128 v[128:131], v154
	ds_read_b128 v[142:145], v154 offset:1024
	ds_read_b128 v[146:149], v154 offset:2048
	ds_read_b128 v[154:157], v154 offset:3072
	ds_read_b128 v[158:161], v170
	ds_read_b128 v[162:165], v170 offset:1024
	ds_read_b128 v[166:169], v170 offset:2048
	ds_read_b128 v[170:173], v170 offset:3072
	ds_read_b128 v[174:177], v153 offset:32768
	ds_read_b128 v[178:181], v153 offset:33792
	ds_read_b128 v[182:185], v153 offset:34816
	ds_read_b128 v[186:189], v153 offset:35840
	ds_read_b128 v[190:193], v153 offset:36864
	ds_read_b128 v[194:197], v153 offset:37888
	ds_read_b128 v[198:201], v153 offset:38912
	ds_read_b128 v[202:205], v153 offset:39936
	s_waitcnt vmcnt(8)
	s_waitcnt lgkmcnt(0)
	s_barrier
	s_setprio 1
	s_waitcnt lgkmcnt(0)
	v_mfma_f32_16x16x32_bf16 v[124:127], v[128:131], v[174:177], v[124:127]
	v_mfma_f32_16x16x32_bf16 v[124:127], v[142:145], v[178:181], v[124:127]
	v_mfma_f32_16x16x32_bf16 v[120:123], v[146:149], v[174:177], v[120:123]
	v_mfma_f32_16x16x32_bf16 v[120:123], v[154:157], v[178:181], v[120:123]
	v_mfma_f32_16x16x32_bf16 v[116:119], v[128:131], v[182:185], v[116:119]
	v_mfma_f32_16x16x32_bf16 v[116:119], v[142:145], v[186:189], v[116:119]
	v_mfma_f32_16x16x32_bf16 v[112:115], v[146:149], v[182:185], v[112:115]
	v_mfma_f32_16x16x32_bf16 v[112:115], v[154:157], v[186:189], v[112:115]
	v_mfma_f32_16x16x32_bf16 v[108:111], v[128:131], v[190:193], v[108:111]
	v_mfma_f32_16x16x32_bf16 v[108:111], v[142:145], v[194:197], v[108:111]
	v_mfma_f32_16x16x32_bf16 v[104:107], v[146:149], v[190:193], v[104:107]
	v_mfma_f32_16x16x32_bf16 v[104:107], v[154:157], v[194:197], v[104:107]
	v_mfma_f32_16x16x32_bf16 v[100:103], v[128:131], v[198:201], v[100:103]
	v_mfma_f32_16x16x32_bf16 v[100:103], v[142:145], v[202:205], v[100:103]
	v_mfma_f32_16x16x32_bf16 v[96:99], v[146:149], v[198:201], v[96:99]
	v_mfma_f32_16x16x32_bf16 v[96:99], v[154:157], v[202:205], v[96:99]
	s_setprio 0
	s_setprio 1
	v_mfma_f32_16x16x32_bf16 v[92:95], v[158:161], v[174:177], v[92:95]
	v_mfma_f32_16x16x32_bf16 v[92:95], v[162:165], v[178:181], v[92:95]
	v_mfma_f32_16x16x32_bf16 v[88:91], v[166:169], v[174:177], v[88:91]
	v_mfma_f32_16x16x32_bf16 v[88:91], v[170:173], v[178:181], v[88:91]
	v_mfma_f32_16x16x32_bf16 v[84:87], v[158:161], v[182:185], v[84:87]
	v_mfma_f32_16x16x32_bf16 v[84:87], v[162:165], v[186:189], v[84:87]
	v_mfma_f32_16x16x32_bf16 v[80:83], v[166:169], v[182:185], v[80:83]
	v_mfma_f32_16x16x32_bf16 v[80:83], v[170:173], v[186:189], v[80:83]
	v_mfma_f32_16x16x32_bf16 v[76:79], v[158:161], v[190:193], v[76:79]
	v_mfma_f32_16x16x32_bf16 v[76:79], v[162:165], v[194:197], v[76:79]
	v_mfma_f32_16x16x32_bf16 v[72:75], v[166:169], v[190:193], v[72:75]
	v_mfma_f32_16x16x32_bf16 v[72:75], v[170:173], v[194:197], v[72:75]
	s_setprio 2
	s_barrier
	v_mfma_f32_16x16x32_bf16 v[68:71], v[158:161], v[198:201], v[68:71]
	v_mfma_f32_16x16x32_bf16 v[68:71], v[162:165], v[202:205], v[68:71]
	v_mfma_f32_16x16x32_bf16 v[64:67], v[166:169], v[198:201], v[64:67]
	v_mfma_f32_16x16x32_bf16 v[64:67], v[170:173], v[202:205], v[64:67]
	s_setprio 0
	s_add_i32 s50, s50, s14
	s_mov_b32 m0, s50
	s_add_u32 s98, s78, s24
	s_addc_u32 s99, s79, s25
	global_load_lds_dwordx4 v134, s[98:99]
	s_add_i32 m0, s50, 0x2000
	s_add_i32 s50, s51, s14
	s_add_u32 s98, s78, s34
	s_addc_u32 s99, s79, s35
	global_load_lds_dwordx4 v134, s[98:99]
	s_mov_b32 m0, s50
	s_add_u32 s98, s78, s36
	s_addc_u32 s99, s79, s37
	global_load_lds_dwordx4 v134, s[98:99]
	s_add_i32 m0, s50, 0x2000
	s_nop 0
	s_add_u32 s98, s78, s38
	s_addc_u32 s99, s79, s39
	global_load_lds_dwordx4 v134, s[98:99]
	s_mov_b32 m0, s66
	s_nop 0
	s_add_u32 s98, s76, s24
	s_addc_u32 s99, s77, s25
	global_load_lds_dwordx4 v132, s[98:99]
	s_mov_b32 m0, s67
	s_nop 0
	s_add_u32 s98, s76, s34
	s_addc_u32 s99, s77, s35
	global_load_lds_dwordx4 v132, s[98:99]
	ds_read_b128 v[174:177], v153 offset:49152
	ds_read_b128 v[178:181], v153 offset:50176
	ds_read_b128 v[182:185], v153 offset:51200
	ds_read_b128 v[186:189], v153 offset:52224
	ds_read_b128 v[190:193], v153 offset:53248
	ds_read_b128 v[194:197], v153 offset:54272
	ds_read_b128 v[198:201], v153 offset:55296
	ds_read_b128 v[202:205], v153 offset:56320
	s_waitcnt vmcnt(8)
	s_waitcnt lgkmcnt(0)
	s_barrier
	s_setprio 1
	s_waitcnt lgkmcnt(0)
	v_mfma_f32_16x16x32_bf16 v[60:63], v[128:131], v[174:177], v[60:63]
	v_mfma_f32_16x16x32_bf16 v[60:63], v[142:145], v[178:181], v[60:63]
	v_mfma_f32_16x16x32_bf16 v[56:59], v[146:149], v[174:177], v[56:59]
	v_mfma_f32_16x16x32_bf16 v[56:59], v[154:157], v[178:181], v[56:59]
	v_mfma_f32_16x16x32_bf16 v[52:55], v[128:131], v[182:185], v[52:55]
	v_mfma_f32_16x16x32_bf16 v[52:55], v[142:145], v[186:189], v[52:55]
	v_mfma_f32_16x16x32_bf16 v[48:51], v[146:149], v[182:185], v[48:51]
	v_mfma_f32_16x16x32_bf16 v[48:51], v[154:157], v[186:189], v[48:51]
	v_mfma_f32_16x16x32_bf16 v[44:47], v[128:131], v[190:193], v[44:47]
	v_mfma_f32_16x16x32_bf16 v[44:47], v[142:145], v[194:197], v[44:47]
	v_mfma_f32_16x16x32_bf16 v[40:43], v[146:149], v[190:193], v[40:43]
	v_mfma_f32_16x16x32_bf16 v[40:43], v[154:157], v[194:197], v[40:43]
	v_mfma_f32_16x16x32_bf16 v[36:39], v[128:131], v[198:201], v[36:39]
	v_mfma_f32_16x16x32_bf16 v[36:39], v[142:145], v[202:205], v[36:39]
	v_mfma_f32_16x16x32_bf16 v[32:35], v[146:149], v[198:201], v[32:35]
	v_mfma_f32_16x16x32_bf16 v[32:35], v[154:157], v[202:205], v[32:35]
	s_setprio 0
	s_setprio 1
	v_mfma_f32_16x16x32_bf16 v[28:31], v[158:161], v[174:177], v[28:31]
	v_mfma_f32_16x16x32_bf16 v[28:31], v[162:165], v[178:181], v[28:31]
	v_mfma_f32_16x16x32_bf16 v[24:27], v[166:169], v[174:177], v[24:27]
	v_mfma_f32_16x16x32_bf16 v[24:27], v[170:173], v[178:181], v[24:27]
	v_mfma_f32_16x16x32_bf16 v[20:23], v[158:161], v[182:185], v[20:23]
	v_mfma_f32_16x16x32_bf16 v[20:23], v[162:165], v[186:189], v[20:23]
	v_mfma_f32_16x16x32_bf16 v[16:19], v[166:169], v[182:185], v[16:19]
	v_mfma_f32_16x16x32_bf16 v[16:19], v[170:173], v[186:189], v[16:19]
	v_mfma_f32_16x16x32_bf16 v[12:15], v[158:161], v[190:193], v[12:15]
	v_mfma_f32_16x16x32_bf16 v[12:15], v[162:165], v[194:197], v[12:15]
	v_mfma_f32_16x16x32_bf16 v[8:11], v[166:169], v[190:193], v[8:11]
	v_mfma_f32_16x16x32_bf16 v[8:11], v[170:173], v[194:197], v[8:11]
	s_setprio 2
	s_barrier
	v_mfma_f32_16x16x32_bf16 v[4:7], v[158:161], v[198:201], v[4:7]
	v_mfma_f32_16x16x32_bf16 v[4:7], v[162:165], v[202:205], v[4:7]
	v_mfma_f32_16x16x32_bf16 v[0:3], v[166:169], v[198:201], v[0:3]
	v_mfma_f32_16x16x32_bf16 v[0:3], v[170:173], v[202:205], v[0:3]
	s_setprio 0
	s_add_i32 s62, s62, 2
	s_add_u32 s74, s74, 0x100
	s_addc_u32 s75, s75, 0
	s_add_u32 s60, s60, 0x100
	s_addc_u32 s61, s61, 0
	s_cmp_gt_u32 s62, 61
	s_cbranch_scc0 .LBB0_627
	s_and_b64 vcc, exec, s[40:41]
	s_cbranch_vccz .LBB0_630
	s_barrier

.Lcm4_skip:
.LBB0_800:
	s_add_u32 s9, s6, 0xfff80080
	s_addc_u32 s50, s7, -1
	s_cmp_eq_u32 s8, 28
	s_cselect_b32 vcc_hi, s5, s50
	s_cselect_b32 vcc_lo, s10, s9
	s_cselect_b32 s51, s11, s78
	s_cselect_b32 s50, s73, s75
	s_add_i32 m0, s65, 0xc000
	s_nop 0
	global_load_lds_dwordx4 v178, s[6:7]
	s_add_i32 m0, s65, 0xe000
	s_nop 0
	s_add_u32 s98, s6, s36
	s_addc_u32 s99, s7, s37
	global_load_lds_dwordx4 v178, s[98:99]
	ds_read_b128 v[128:131], v187
	ds_read_b128 v[132:135], v187 offset:1024
	ds_read_b128 v[136:139], v187 offset:2048
	ds_read_b128 v[140:143], v187 offset:3072
	ds_read_b128 v[144:147], v188
	ds_read_b128 v[148:151], v188 offset:1024
	ds_read_b128 v[152:155], v188 offset:2048
	ds_read_b128 v[156:159], v188 offset:3072
	ds_read_b128 v[160:163], v189
	ds_read_b128 v[164:167], v189 offset:1024
	ds_read_b128 v[168:171], v189 offset:2048
	ds_read_b128 v[192:195], v189 offset:3072
	ds_read_b128 v[196:199], v189 offset:4096
	ds_read_b128 v[200:203], v189 offset:5120
	ds_read_b128 v[204:207], v189 offset:6144
	ds_read_b128 v[208:211], v189 offset:7168
	s_waitcnt vmcnt(8)
	s_waitcnt lgkmcnt(0)
	s_barrier
	s_setprio 1
	s_waitcnt lgkmcnt(0)
	v_mfma_i32_16x16x64_i8 v[84:87], v[128:131], v[160:163], v[84:87]
	v_mfma_i32_16x16x64_i8 v[84:87], v[132:135], v[164:167], v[84:87]
	v_mfma_i32_16x16x64_i8 v[16:19], v[136:139], v[160:163], v[16:19]
	v_mfma_i32_16x16x64_i8 v[16:19], v[140:143], v[164:167], v[16:19]
	v_mfma_i32_16x16x64_i8 v[88:91], v[128:131], v[168:171], v[88:91]
	v_mfma_i32_16x16x64_i8 v[88:91], v[132:135], v[192:195], v[88:91]
	v_mfma_i32_16x16x64_i8 v[20:23], v[136:139], v[168:171], v[20:23]
	v_mfma_i32_16x16x64_i8 v[20:23], v[140:143], v[192:195], v[20:23]
	v_mfma_i32_16x16x64_i8 v[92:95], v[128:131], v[196:199], v[92:95]
	v_mfma_i32_16x16x64_i8 v[92:95], v[132:135], v[200:203], v[92:95]
	v_mfma_i32_16x16x64_i8 v[24:27], v[136:139], v[196:199], v[24:27]
	v_mfma_i32_16x16x64_i8 v[24:27], v[140:143], v[200:203], v[24:27]
	v_mfma_i32_16x16x64_i8 v[96:99], v[128:131], v[204:207], v[96:99]
	v_mfma_i32_16x16x64_i8 v[96:99], v[132:135], v[208:211], v[96:99]
	v_mfma_i32_16x16x64_i8 v[28:31], v[136:139], v[204:207], v[28:31]
	v_mfma_i32_16x16x64_i8 v[28:31], v[140:143], v[208:211], v[28:31]
	s_setprio 0
	s_setprio 1
	v_mfma_i32_16x16x64_i8 v[124:127], v[144:147], v[160:163], v[124:127]
	v_mfma_i32_16x16x64_i8 v[124:127], v[148:151], v[164:167], v[124:127]
	v_mfma_i32_16x16x64_i8 v[68:71], v[152:155], v[160:163], v[68:71]
	v_mfma_i32_16x16x64_i8 v[68:71], v[156:159], v[164:167], v[68:71]
	v_mfma_i32_16x16x64_i8 v[120:123], v[144:147], v[168:171], v[120:123]
	v_mfma_i32_16x16x64_i8 v[120:123], v[148:151], v[192:195], v[120:123]
	v_mfma_i32_16x16x64_i8 v[72:75], v[152:155], v[168:171], v[72:75]
	v_mfma_i32_16x16x64_i8 v[72:75], v[156:159], v[192:195], v[72:75]
	v_mfma_i32_16x16x64_i8 v[116:119], v[144:147], v[196:199], v[116:119]
	v_mfma_i32_16x16x64_i8 v[116:119], v[148:151], v[200:203], v[116:119]
	v_mfma_i32_16x16x64_i8 v[80:83], v[152:155], v[196:199], v[80:83]
	v_mfma_i32_16x16x64_i8 v[80:83], v[156:159], v[200:203], v[80:83]
	s_setprio 2
	s_barrier
	v_mfma_i32_16x16x64_i8 v[112:115], v[144:147], v[204:207], v[112:115]
	v_mfma_i32_16x16x64_i8 v[112:115], v[148:151], v[208:211], v[112:115]
	v_mfma_i32_16x16x64_i8 v[60:63], v[152:155], v[204:207], v[60:63]
	v_mfma_i32_16x16x64_i8 v[60:63], v[156:159], v[208:211], v[60:63]
	s_setprio 0
	s_add_i32 s9, s80, s33
	s_mov_b64 s[100:101], s[50:51]
	s_mov_b32 m0, s9
	s_nop 0
	global_load_lds_dwordx4 v174, s[50:51]
	s_add_i32 m0, s9, 0x2000
	s_add_i32 s9, s81, s33
	s_add_u32 s98, s50, s36
	s_addc_u32 s99, s51, s37
	global_load_lds_dwordx4 v174, s[98:99]
	s_mov_b32 m0, s9
	s_nop 0
	s_add_u32 s98, s50, s38
	s_addc_u32 s99, s51, s39
	global_load_lds_dwordx4 v174, s[98:99]
	s_add_i32 m0, s9, 0x2000
	s_nop 0
	s_add_u32 s98, s50, s40
	s_addc_u32 s99, s51, s41
	global_load_lds_dwordx4 v174, s[98:99]
	s_mov_b32 m0, s65
	s_nop 0
	global_load_lds_dwordx4 v172, vcc
	s_mov_b32 m0, s67
	s_nop 0
	s_add_u32 s98, vcc_lo, s36
	s_addc_u32 s99, vcc_hi, s37
	global_load_lds_dwordx4 v172, s[98:99]
	ds_read_b128 v[160:163], v189 offset:16384
	ds_read_b128 v[164:167], v189 offset:17408
	ds_read_b128 v[168:171], v189 offset:18432
	ds_read_b128 v[192:195], v189 offset:19456
	ds_read_b128 v[196:199], v189 offset:20480
	ds_read_b128 v[200:203], v189 offset:21504
	ds_read_b128 v[204:207], v189 offset:22528
	ds_read_b128 v[208:211], v189 offset:23552
	s_waitcnt vmcnt(8)
	s_waitcnt lgkmcnt(0)
	s_barrier
	s_setprio 1
	s_waitcnt lgkmcnt(0)
	v_mfma_i32_16x16x64_i8 v[48:51], v[128:131], v[160:163], v[48:51]
	v_mfma_i32_16x16x64_i8 v[48:51], v[132:135], v[164:167], v[48:51]
	v_mfma_i32_16x16x64_i8 v[0:3], v[136:139], v[160:163], v[0:3]
	v_mfma_i32_16x16x64_i8 v[0:3], v[140:143], v[164:167], v[0:3]
	v_mfma_i32_16x16x64_i8 v[52:55], v[128:131], v[168:171], v[52:55]
	v_mfma_i32_16x16x64_i8 v[52:55], v[132:135], v[192:195], v[52:55]
	v_mfma_i32_16x16x64_i8 v[4:7], v[136:139], v[168:171], v[4:7]
	v_mfma_i32_16x16x64_i8 v[4:7], v[140:143], v[192:195], v[4:7]
	v_mfma_i32_16x16x64_i8 v[56:59], v[128:131], v[196:199], v[56:59]
	v_mfma_i32_16x16x64_i8 v[56:59], v[132:135], v[200:203], v[56:59]
	v_mfma_i32_16x16x64_i8 v[8:11], v[136:139], v[196:199], v[8:11]
	v_mfma_i32_16x16x64_i8 v[8:11], v[140:143], v[200:203], v[8:11]
	v_mfma_i32_16x16x64_i8 v[64:67], v[128:131], v[204:207], v[64:67]
	v_mfma_i32_16x16x64_i8 v[64:67], v[132:135], v[208:211], v[64:67]
	v_mfma_i32_16x16x64_i8 v[12:15], v[136:139], v[204:207], v[12:15]
	v_mfma_i32_16x16x64_i8 v[12:15], v[140:143], v[208:211], v[12:15]
	s_setprio 0
	s_setprio 1
	v_mfma_i32_16x16x64_i8 v[108:111], v[144:147], v[160:163], v[108:111]
	v_mfma_i32_16x16x64_i8 v[108:111], v[148:151], v[164:167], v[108:111]
	v_mfma_i32_16x16x64_i8 v[44:47], v[152:155], v[160:163], v[44:47]
	v_mfma_i32_16x16x64_i8 v[44:47], v[156:159], v[164:167], v[44:47]
	v_mfma_i32_16x16x64_i8 v[104:107], v[144:147], v[168:171], v[104:107]
	v_mfma_i32_16x16x64_i8 v[104:107], v[148:151], v[192:195], v[104:107]
	v_mfma_i32_16x16x64_i8 v[40:43], v[152:155], v[168:171], v[40:43]
	v_mfma_i32_16x16x64_i8 v[40:43], v[156:159], v[192:195], v[40:43]
	v_mfma_i32_16x16x64_i8 v[100:103], v[144:147], v[196:199], v[100:103]
	v_mfma_i32_16x16x64_i8 v[100:103], v[148:151], v[200:203], v[100:103]
	v_mfma_i32_16x16x64_i8 v[32:35], v[152:155], v[196:199], v[32:35]
	v_mfma_i32_16x16x64_i8 v[32:35], v[156:159], v[200:203], v[32:35]
	s_setprio 2
	s_barrier
	v_mfma_i32_16x16x64_i8 v[76:79], v[144:147], v[204:207], v[76:79]
	v_mfma_i32_16x16x64_i8 v[76:79], v[148:151], v[208:211], v[76:79]
	v_mfma_i32_16x16x64_i8 v[36:39], v[152:155], v[204:207], v[36:39]
	v_mfma_i32_16x16x64_i8 v[36:39], v[156:159], v[208:211], v[36:39]
	s_setprio 0
	s_mov_b32 m0, s71
	s_add_u32 s98, vcc_lo, s38
	s_addc_u32 s99, vcc_hi, s39
	global_load_lds_dwordx4 v172, s[98:99]
	s_mov_b32 m0, s82
	s_nop 0
	s_add_u32 s98, vcc_lo, s40
	s_addc_u32 s99, vcc_hi, s41
	global_load_lds_dwordx4 v172, s[98:99]
	s_add_i32 s9, 0, 0x18000
	s_add_i32 s50, 0, 0x1c000
	v_add_u32_e32 v140, s9, v186
	v_add_u32_e32 v156, s50, v186
	ds_read_b128 v[128:131], v140
	ds_read_b128 v[132:135], v140 offset:1024
	ds_read_b128 v[136:139], v140 offset:2048
	ds_read_b128 v[140:143], v140 offset:3072
	ds_read_b128 v[144:147], v156
	ds_read_b128 v[148:151], v156 offset:1024
	ds_read_b128 v[152:155], v156 offset:2048
	ds_read_b128 v[156:159], v156 offset:3072
	ds_read_b128 v[160:163], v189 offset:32768
	ds_read_b128 v[164:167], v189 offset:33792
	ds_read_b128 v[168:171], v189 offset:34816
	ds_read_b128 v[192:195], v189 offset:35840
	ds_read_b128 v[196:199], v189 offset:36864
	ds_read_b128 v[200:203], v189 offset:37888
	ds_read_b128 v[204:207], v189 offset:38912
	ds_read_b128 v[208:211], v189 offset:39936
	s_waitcnt vmcnt(8)
	s_waitcnt lgkmcnt(0)
	s_barrier
	s_setprio 1
	s_waitcnt lgkmcnt(0)
	v_mfma_i32_16x16x64_i8 v[84:87], v[128:131], v[160:163], v[84:87]
	v_mfma_i32_16x16x64_i8 v[84:87], v[132:135], v[164:167], v[84:87]
	v_mfma_i32_16x16x64_i8 v[16:19], v[136:139], v[160:163], v[16:19]
	v_mfma_i32_16x16x64_i8 v[16:19], v[140:143], v[164:167], v[16:19]
	v_mfma_i32_16x16x64_i8 v[88:91], v[128:131], v[168:171], v[88:91]
	v_mfma_i32_16x16x64_i8 v[88:91], v[132:135], v[192:195], v[88:91]
	v_mfma_i32_16x16x64_i8 v[20:23], v[136:139], v[168:171], v[20:23]
	v_mfma_i32_16x16x64_i8 v[20:23], v[140:143], v[192:195], v[20:23]
	v_mfma_i32_16x16x64_i8 v[92:95], v[128:131], v[196:199], v[92:95]
	v_mfma_i32_16x16x64_i8 v[92:95], v[132:135], v[200:203], v[92:95]
	v_mfma_i32_16x16x64_i8 v[24:27], v[136:139], v[196:199], v[24:27]
	v_mfma_i32_16x16x64_i8 v[24:27], v[140:143], v[200:203], v[24:27]
	v_mfma_i32_16x16x64_i8 v[96:99], v[128:131], v[204:207], v[96:99]
	v_mfma_i32_16x16x64_i8 v[96:99], v[132:135], v[208:211], v[96:99]
	v_mfma_i32_16x16x64_i8 v[28:31], v[136:139], v[204:207], v[28:31]
	v_mfma_i32_16x16x64_i8 v[28:31], v[140:143], v[208:211], v[28:31]
	s_setprio 0
	s_setprio 1
	v_mfma_i32_16x16x64_i8 v[124:127], v[144:147], v[160:163], v[124:127]
	v_mfma_i32_16x16x64_i8 v[124:127], v[148:151], v[164:167], v[124:127]
	v_mfma_i32_16x16x64_i8 v[68:71], v[152:155], v[160:163], v[68:71]
	v_mfma_i32_16x16x64_i8 v[68:71], v[156:159], v[164:167], v[68:71]
	v_mfma_i32_16x16x64_i8 v[120:123], v[144:147], v[168:171], v[120:123]
	v_mfma_i32_16x16x64_i8 v[120:123], v[148:151], v[192:195], v[120:123]
	v_mfma_i32_16x16x64_i8 v[72:75], v[152:155], v[168:171], v[72:75]
	v_mfma_i32_16x16x64_i8 v[72:75], v[156:159], v[192:195], v[72:75]
	v_mfma_i32_16x16x64_i8 v[116:119], v[144:147], v[196:199], v[116:119]
	v_mfma_i32_16x16x64_i8 v[116:119], v[148:151], v[200:203], v[116:119]
	v_mfma_i32_16x16x64_i8 v[80:83], v[152:155], v[196:199], v[80:83]
	v_mfma_i32_16x16x64_i8 v[80:83], v[156:159], v[200:203], v[80:83]
	s_setprio 2
	s_barrier
	v_mfma_i32_16x16x64_i8 v[112:115], v[144:147], v[204:207], v[112:115]
	v_mfma_i32_16x16x64_i8 v[112:115], v[148:151], v[208:211], v[112:115]
	v_mfma_i32_16x16x64_i8 v[60:63], v[152:155], v[204:207], v[60:63]
	v_mfma_i32_16x16x64_i8 v[60:63], v[156:159], v[208:211], v[60:63]
	s_setprio 0
	s_add_i32 s9, s9, s33
	s_mov_b32 m0, s9
	s_add_u32 s98, s100, s44
	s_addc_u32 s99, s101, s45
	global_load_lds_dwordx4 v174, s[98:99]
	s_add_i32 m0, s9, 0x2000
	s_add_i32 s9, s50, s33
	s_add_u32 s98, s100, s46
	s_addc_u32 s99, s101, s47
	global_load_lds_dwordx4 v174, s[98:99]
	s_mov_b32 m0, s9
	s_add_u32 s98, s100, s48
	s_addc_u32 s99, s101, s49
	global_load_lds_dwordx4 v174, s[98:99]
	s_add_i32 m0, s9, 0x2000
	s_nop 0
	s_add_u32 s98, s100, s52
	s_addc_u32 s99, s101, s53
	global_load_lds_dwordx4 v174, s[98:99]
	s_mov_b32 m0, s90
	s_nop 0
	s_add_u32 s98, vcc_lo, s44
	s_addc_u32 s99, vcc_hi, s45
	global_load_lds_dwordx4 v172, s[98:99]
	s_mov_b32 m0, s91
	s_nop 0
	s_add_u32 s98, vcc_lo, s46
	s_addc_u32 s99, vcc_hi, s47
	global_load_lds_dwordx4 v172, s[98:99]
	ds_read_b128 v[160:163], v189 offset:49152
	ds_read_b128 v[164:167], v189 offset:50176
	ds_read_b128 v[168:171], v189 offset:51200
	ds_read_b128 v[192:195], v189 offset:52224
	ds_read_b128 v[196:199], v189 offset:53248
	ds_read_b128 v[200:203], v189 offset:54272
	ds_read_b128 v[204:207], v189 offset:55296
	ds_read_b128 v[208:211], v189 offset:56320
	s_waitcnt vmcnt(8)
	s_waitcnt lgkmcnt(0)
	s_barrier
	s_setprio 1
	s_waitcnt lgkmcnt(0)
	v_mfma_i32_16x16x64_i8 v[48:51], v[128:131], v[160:163], v[48:51]
	v_mfma_i32_16x16x64_i8 v[48:51], v[132:135], v[164:167], v[48:51]
	v_mfma_i32_16x16x64_i8 v[0:3], v[136:139], v[160:163], v[0:3]
	v_mfma_i32_16x16x64_i8 v[0:3], v[140:143], v[164:167], v[0:3]
	v_mfma_i32_16x16x64_i8 v[52:55], v[128:131], v[168:171], v[52:55]
	v_mfma_i32_16x16x64_i8 v[52:55], v[132:135], v[192:195], v[52:55]
	v_mfma_i32_16x16x64_i8 v[4:7], v[136:139], v[168:171], v[4:7]
	v_mfma_i32_16x16x64_i8 v[4:7], v[140:143], v[192:195], v[4:7]
	v_mfma_i32_16x16x64_i8 v[56:59], v[128:131], v[196:199], v[56:59]
	v_mfma_i32_16x16x64_i8 v[56:59], v[132:135], v[200:203], v[56:59]
	v_mfma_i32_16x16x64_i8 v[8:11], v[136:139], v[196:199], v[8:11]
	v_mfma_i32_16x16x64_i8 v[8:11], v[140:143], v[200:203], v[8:11]
	v_mfma_i32_16x16x64_i8 v[64:67], v[128:131], v[204:207], v[64:67]
	v_mfma_i32_16x16x64_i8 v[64:67], v[132:135], v[208:211], v[64:67]
	v_mfma_i32_16x16x64_i8 v[12:15], v[136:139], v[204:207], v[12:15]
	v_mfma_i32_16x16x64_i8 v[12:15], v[140:143], v[208:211], v[12:15]
	s_setprio 0
	s_setprio 1
	v_mfma_i32_16x16x64_i8 v[108:111], v[144:147], v[160:163], v[108:111]
	v_mfma_i32_16x16x64_i8 v[108:111], v[148:151], v[164:167], v[108:111]
	v_mfma_i32_16x16x64_i8 v[44:47], v[152:155], v[160:163], v[44:47]
	v_mfma_i32_16x16x64_i8 v[44:47], v[156:159], v[164:167], v[44:47]
	v_mfma_i32_16x16x64_i8 v[104:107], v[144:147], v[168:171], v[104:107]
	v_mfma_i32_16x16x64_i8 v[104:107], v[148:151], v[192:195], v[104:107]
	v_mfma_i32_16x16x64_i8 v[40:43], v[152:155], v[168:171], v[40:43]
	v_mfma_i32_16x16x64_i8 v[40:43], v[156:159], v[192:195], v[40:43]
	v_mfma_i32_16x16x64_i8 v[100:103], v[144:147], v[196:199], v[100:103]
	v_mfma_i32_16x16x64_i8 v[100:103], v[148:151], v[200:203], v[100:103]
	v_mfma_i32_16x16x64_i8 v[32:35], v[152:155], v[196:199], v[32:35]
	v_mfma_i32_16x16x64_i8 v[32:35], v[156:159], v[200:203], v[32:35]
	s_setprio 2
	s_barrier
	v_mfma_i32_16x16x64_i8 v[76:79], v[144:147], v[204:207], v[76:79]
	v_mfma_i32_16x16x64_i8 v[76:79], v[148:151], v[208:211], v[76:79]
	v_mfma_i32_16x16x64_i8 v[36:39], v[152:155], v[204:207], v[36:39]
	v_mfma_i32_16x16x64_i8 v[36:39], v[156:159], v[208:211], v[36:39]
	s_setprio 0
	s_add_i32 s8, s8, 2
	s_add_u32 s75, s75, 0x100
	s_addc_u32 s78, s78, 0
	s_add_u32 s6, s6, 0x100
	s_addc_u32 s7, s7, 0
	s_cmp_gt_u32 s8, 29
	s_cbranch_scc0 .LBB0_800
	s_and_b64 vcc, exec, s[54:55]
	s_cbranch_vccz .LBB0_803
	s_barrier

.LBB0_1034:
	s_add_u32 s47, s44, 0xffd50080
	s_addc_u32 s64, s45, -1
	s_cmpk_eq_i32 s46, 0xa8
	s_cselect_b32 s65, s5, s64
	s_cselect_b32 s64, s4, s47
	s_cselect_b32 s67, s43, s63
	s_cselect_b32 s66, s42, s62
	s_add_i32 m0, s25, 0xc000
	s_nop 0
	global_load_lds_dwordx4 v132, s[44:45]
	s_add_i32 m0, s25, 0xe000
	s_nop 0
	s_add_u32 s98, s44, s0
	s_addc_u32 s99, s45, s1
	global_load_lds_dwordx4 v132, s[98:99]
	ds_read_b128 v[138:141], v151
	ds_read_b128 v[142:145], v151 offset:1024
	ds_read_b128 v[146:149], v151 offset:2048
	ds_read_b128 v[154:157], v151 offset:3072
	ds_read_b128 v[158:161], v152
	ds_read_b128 v[162:165], v152 offset:1024
	ds_read_b128 v[166:169], v152 offset:2048
	ds_read_b128 v[170:173], v152 offset:3072
	ds_read_b128 v[174:177], v153
	ds_read_b128 v[178:181], v153 offset:1024
	ds_read_b128 v[182:185], v153 offset:2048
	ds_read_b128 v[186:189], v153 offset:3072
	ds_read_b128 v[190:193], v153 offset:4096
	ds_read_b128 v[194:197], v153 offset:5120
	ds_read_b128 v[198:201], v153 offset:6144
	ds_read_b128 v[202:205], v153 offset:7168
	s_waitcnt vmcnt(8)
	s_waitcnt lgkmcnt(0)
	s_barrier
	s_setprio 1
	s_waitcnt lgkmcnt(0)
	v_mfma_f32_16x16x32_bf16 v[124:127], v[138:141], v[174:177], v[124:127]
	v_mfma_f32_16x16x32_bf16 v[124:127], v[142:145], v[178:181], v[124:127]
	v_mfma_f32_16x16x32_bf16 v[120:123], v[146:149], v[174:177], v[120:123]
	v_mfma_f32_16x16x32_bf16 v[120:123], v[154:157], v[178:181], v[120:123]
	v_mfma_f32_16x16x32_bf16 v[116:119], v[138:141], v[182:185], v[116:119]
	v_mfma_f32_16x16x32_bf16 v[116:119], v[142:145], v[186:189], v[116:119]
	v_mfma_f32_16x16x32_bf16 v[112:115], v[146:149], v[182:185], v[112:115]
	v_mfma_f32_16x16x32_bf16 v[112:115], v[154:157], v[186:189], v[112:115]
	v_mfma_f32_16x16x32_bf16 v[108:111], v[138:141], v[190:193], v[108:111]
	v_mfma_f32_16x16x32_bf16 v[108:111], v[142:145], v[194:197], v[108:111]
	v_mfma_f32_16x16x32_bf16 v[104:107], v[146:149], v[190:193], v[104:107]
	v_mfma_f32_16x16x32_bf16 v[104:107], v[154:157], v[194:197], v[104:107]
	v_mfma_f32_16x16x32_bf16 v[100:103], v[138:141], v[198:201], v[100:103]
	v_mfma_f32_16x16x32_bf16 v[100:103], v[142:145], v[202:205], v[100:103]
	v_mfma_f32_16x16x32_bf16 v[96:99], v[146:149], v[198:201], v[96:99]
	v_mfma_f32_16x16x32_bf16 v[96:99], v[154:157], v[202:205], v[96:99]
	s_setprio 0
	s_setprio 1
	v_mfma_f32_16x16x32_bf16 v[92:95], v[158:161], v[174:177], v[92:95]
	v_mfma_f32_16x16x32_bf16 v[92:95], v[162:165], v[178:181], v[92:95]
	v_mfma_f32_16x16x32_bf16 v[88:91], v[166:169], v[174:177], v[88:91]
	v_mfma_f32_16x16x32_bf16 v[88:91], v[170:173], v[178:181], v[88:91]
	v_mfma_f32_16x16x32_bf16 v[84:87], v[158:161], v[182:185], v[84:87]
	v_mfma_f32_16x16x32_bf16 v[84:87], v[162:165], v[186:189], v[84:87]
	v_mfma_f32_16x16x32_bf16 v[80:83], v[166:169], v[182:185], v[80:83]
	v_mfma_f32_16x16x32_bf16 v[80:83], v[170:173], v[186:189], v[80:83]
	v_mfma_f32_16x16x32_bf16 v[76:79], v[158:161], v[190:193], v[76:79]
	v_mfma_f32_16x16x32_bf16 v[76:79], v[162:165], v[194:197], v[76:79]
	v_mfma_f32_16x16x32_bf16 v[72:75], v[166:169], v[190:193], v[72:75]
	v_mfma_f32_16x16x32_bf16 v[72:75], v[170:173], v[194:197], v[72:75]
	s_setprio 2
	s_barrier
	v_mfma_f32_16x16x32_bf16 v[68:71], v[158:161], v[198:201], v[68:71]
	v_mfma_f32_16x16x32_bf16 v[68:71], v[162:165], v[202:205], v[68:71]
	v_mfma_f32_16x16x32_bf16 v[64:67], v[166:169], v[198:201], v[64:67]
	v_mfma_f32_16x16x32_bf16 v[64:67], v[170:173], v[202:205], v[64:67]
	s_setprio 0
	s_add_i32 s47, s56, s24
	s_mov_b32 m0, s47
	s_nop 0
	global_load_lds_dwordx4 v130, s[66:67]
	s_add_i32 m0, s47, 0x2000
	s_add_i32 s47, s57, s24
	s_add_u32 s98, s66, s0
	s_addc_u32 s99, s67, s1
	global_load_lds_dwordx4 v130, s[98:99]
	s_mov_b32 m0, s47
	s_nop 0
	s_add_u32 s98, s66, s6
	s_addc_u32 s99, s67, s7
	global_load_lds_dwordx4 v130, s[98:99]
	s_add_i32 m0, s47, 0x2000
	s_nop 0
	s_add_u32 s98, s66, s8
	s_addc_u32 s99, s67, s9
	global_load_lds_dwordx4 v130, s[98:99]
	s_mov_b64 s[100:101], s[64:65]
	s_mov_b32 m0, s25
	s_nop 0
	global_load_lds_dwordx4 v128, s[64:65]
	s_mov_b32 m0, s33
	s_nop 0
	s_add_u32 s98, s64, s0
	s_addc_u32 s99, s65, s1
	global_load_lds_dwordx4 v128, s[98:99]
	ds_read_b128 v[174:177], v153 offset:16384
	ds_read_b128 v[178:181], v153 offset:17408
	ds_read_b128 v[182:185], v153 offset:18432
	ds_read_b128 v[186:189], v153 offset:19456
	ds_read_b128 v[190:193], v153 offset:20480
	ds_read_b128 v[194:197], v153 offset:21504
	ds_read_b128 v[198:201], v153 offset:22528
	ds_read_b128 v[202:205], v153 offset:23552
	s_waitcnt vmcnt(8)
	s_waitcnt lgkmcnt(0)
	s_barrier
	s_setprio 1
	s_waitcnt lgkmcnt(0)
	v_mfma_f32_16x16x32_bf16 v[60:63], v[138:141], v[174:177], v[60:63]
	v_mfma_f32_16x16x32_bf16 v[60:63], v[142:145], v[178:181], v[60:63]
	v_mfma_f32_16x16x32_bf16 v[56:59], v[146:149], v[174:177], v[56:59]
	v_mfma_f32_16x16x32_bf16 v[56:59], v[154:157], v[178:181], v[56:59]
	v_mfma_f32_16x16x32_bf16 v[52:55], v[138:141], v[182:185], v[52:55]
	v_mfma_f32_16x16x32_bf16 v[52:55], v[142:145], v[186:189], v[52:55]
	v_mfma_f32_16x16x32_bf16 v[48:51], v[146:149], v[182:185], v[48:51]
	v_mfma_f32_16x16x32_bf16 v[48:51], v[154:157], v[186:189], v[48:51]
	v_mfma_f32_16x16x32_bf16 v[44:47], v[138:141], v[190:193], v[44:47]
	v_mfma_f32_16x16x32_bf16 v[44:47], v[142:145], v[194:197], v[44:47]
	v_mfma_f32_16x16x32_bf16 v[40:43], v[146:149], v[190:193], v[40:43]
	v_mfma_f32_16x16x32_bf16 v[40:43], v[154:157], v[194:197], v[40:43]
	v_mfma_f32_16x16x32_bf16 v[36:39], v[138:141], v[198:201], v[36:39]
	v_mfma_f32_16x16x32_bf16 v[36:39], v[142:145], v[202:205], v[36:39]
	v_mfma_f32_16x16x32_bf16 v[32:35], v[146:149], v[198:201], v[32:35]
	v_mfma_f32_16x16x32_bf16 v[32:35], v[154:157], v[202:205], v[32:35]
	s_setprio 0
	s_setprio 1
	v_mfma_f32_16x16x32_bf16 v[28:31], v[158:161], v[174:177], v[28:31]
	v_mfma_f32_16x16x32_bf16 v[28:31], v[162:165], v[178:181], v[28:31]
	v_mfma_f32_16x16x32_bf16 v[24:27], v[166:169], v[174:177], v[24:27]
	v_mfma_f32_16x16x32_bf16 v[24:27], v[170:173], v[178:181], v[24:27]
	v_mfma_f32_16x16x32_bf16 v[20:23], v[158:161], v[182:185], v[20:23]
	v_mfma_f32_16x16x32_bf16 v[20:23], v[162:165], v[186:189], v[20:23]
	v_mfma_f32_16x16x32_bf16 v[16:19], v[166:169], v[182:185], v[16:19]
	v_mfma_f32_16x16x32_bf16 v[16:19], v[170:173], v[186:189], v[16:19]
	v_mfma_f32_16x16x32_bf16 v[12:15], v[158:161], v[190:193], v[12:15]
	v_mfma_f32_16x16x32_bf16 v[12:15], v[162:165], v[194:197], v[12:15]
	v_mfma_f32_16x16x32_bf16 v[8:11], v[166:169], v[190:193], v[8:11]
	v_mfma_f32_16x16x32_bf16 v[8:11], v[170:173], v[194:197], v[8:11]
	s_setprio 2
	s_barrier
	v_mfma_f32_16x16x32_bf16 v[4:7], v[158:161], v[198:201], v[4:7]
	v_mfma_f32_16x16x32_bf16 v[4:7], v[162:165], v[202:205], v[4:7]
	v_mfma_f32_16x16x32_bf16 v[0:3], v[166:169], v[198:201], v[0:3]
	v_mfma_f32_16x16x32_bf16 v[0:3], v[170:173], v[202:205], v[0:3]
	s_setprio 0
	s_mov_b32 m0, s48
	s_add_u32 s98, s100, s6
	s_addc_u32 s99, s101, s7
	global_load_lds_dwordx4 v128, s[98:99]
	s_mov_b32 m0, s49
	s_nop 0
	s_add_u32 s98, s100, s8
	s_addc_u32 s99, s101, s9
	global_load_lds_dwordx4 v128, s[98:99]
	s_add_i32 s47, 0, 0x18000
	s_add_i32 s64, 0, 0x1c000
	v_add_u32_e32 v154, s47, v150
	v_add_u32_e32 v170, s64, v150
	ds_read_b128 v[138:141], v154
	ds_read_b128 v[142:145], v154 offset:1024
	ds_read_b128 v[146:149], v154 offset:2048
	ds_read_b128 v[154:157], v154 offset:3072
	ds_read_b128 v[158:161], v170
	ds_read_b128 v[162:165], v170 offset:1024
	ds_read_b128 v[166:169], v170 offset:2048
	ds_read_b128 v[170:173], v170 offset:3072
	ds_read_b128 v[174:177], v153 offset:32768
	ds_read_b128 v[178:181], v153 offset:33792
	ds_read_b128 v[182:185], v153 offset:34816
	ds_read_b128 v[186:189], v153 offset:35840
	ds_read_b128 v[190:193], v153 offset:36864
	ds_read_b128 v[194:197], v153 offset:37888
	ds_read_b128 v[198:201], v153 offset:38912
	ds_read_b128 v[202:205], v153 offset:39936
	s_waitcnt vmcnt(8)
	s_waitcnt lgkmcnt(0)
	s_barrier
	s_setprio 1
	s_waitcnt lgkmcnt(0)
	v_mfma_f32_16x16x32_bf16 v[124:127], v[138:141], v[174:177], v[124:127]
	v_mfma_f32_16x16x32_bf16 v[124:127], v[142:145], v[178:181], v[124:127]
	v_mfma_f32_16x16x32_bf16 v[120:123], v[146:149], v[174:177], v[120:123]
	v_mfma_f32_16x16x32_bf16 v[120:123], v[154:157], v[178:181], v[120:123]
	v_mfma_f32_16x16x32_bf16 v[116:119], v[138:141], v[182:185], v[116:119]
	v_mfma_f32_16x16x32_bf16 v[116:119], v[142:145], v[186:189], v[116:119]
	v_mfma_f32_16x16x32_bf16 v[112:115], v[146:149], v[182:185], v[112:115]
	v_mfma_f32_16x16x32_bf16 v[112:115], v[154:157], v[186:189], v[112:115]
	v_mfma_f32_16x16x32_bf16 v[108:111], v[138:141], v[190:193], v[108:111]
	v_mfma_f32_16x16x32_bf16 v[108:111], v[142:145], v[194:197], v[108:111]
	v_mfma_f32_16x16x32_bf16 v[104:107], v[146:149], v[190:193], v[104:107]
	v_mfma_f32_16x16x32_bf16 v[104:107], v[154:157], v[194:197], v[104:107]
	v_mfma_f32_16x16x32_bf16 v[100:103], v[138:141], v[198:201], v[100:103]
	v_mfma_f32_16x16x32_bf16 v[100:103], v[142:145], v[202:205], v[100:103]
	v_mfma_f32_16x16x32_bf16 v[96:99], v[146:149], v[198:201], v[96:99]
	v_mfma_f32_16x16x32_bf16 v[96:99], v[154:157], v[202:205], v[96:99]
	s_setprio 0
	s_setprio 1
	v_mfma_f32_16x16x32_bf16 v[92:95], v[158:161], v[174:177], v[92:95]
	v_mfma_f32_16x16x32_bf16 v[92:95], v[162:165], v[178:181], v[92:95]
	v_mfma_f32_16x16x32_bf16 v[88:91], v[166:169], v[174:177], v[88:91]
	v_mfma_f32_16x16x32_bf16 v[88:91], v[170:173], v[178:181], v[88:91]
	v_mfma_f32_16x16x32_bf16 v[84:87], v[158:161], v[182:185], v[84:87]
	v_mfma_f32_16x16x32_bf16 v[84:87], v[162:165], v[186:189], v[84:87]
	v_mfma_f32_16x16x32_bf16 v[80:83], v[166:169], v[182:185], v[80:83]
	v_mfma_f32_16x16x32_bf16 v[80:83], v[170:173], v[186:189], v[80:83]
	v_mfma_f32_16x16x32_bf16 v[76:79], v[158:161], v[190:193], v[76:79]
	v_mfma_f32_16x16x32_bf16 v[76:79], v[162:165], v[194:197], v[76:79]
	v_mfma_f32_16x16x32_bf16 v[72:75], v[166:169], v[190:193], v[72:75]
	v_mfma_f32_16x16x32_bf16 v[72:75], v[170:173], v[194:197], v[72:75]
	s_setprio 2
	s_barrier
	v_mfma_f32_16x16x32_bf16 v[68:71], v[158:161], v[198:201], v[68:71]
	v_mfma_f32_16x16x32_bf16 v[68:71], v[162:165], v[202:205], v[68:71]
	v_mfma_f32_16x16x32_bf16 v[64:67], v[166:169], v[198:201], v[64:67]
	v_mfma_f32_16x16x32_bf16 v[64:67], v[170:173], v[202:205], v[64:67]
	s_setprio 0
	s_add_i32 s47, s47, s24
	s_mov_b32 m0, s47
	s_add_u32 s98, s66, s16
	s_addc_u32 s99, s67, s17
	global_load_lds_dwordx4 v130, s[98:99]
	s_add_i32 m0, s47, 0x2000
	s_add_i32 s47, s64, s24
	s_add_u32 s98, s66, s20
	s_addc_u32 s99, s67, s21
	global_load_lds_dwordx4 v130, s[98:99]
	s_mov_b32 m0, s47
	s_add_u32 s98, s66, s34
	s_addc_u32 s99, s67, s35
	global_load_lds_dwordx4 v130, s[98:99]
	s_add_i32 m0, s47, 0x2000
	s_nop 0
	s_add_u32 s98, s66, s36
	s_addc_u32 s99, s67, s37
	global_load_lds_dwordx4 v130, s[98:99]
	s_mov_b32 m0, s51
	s_nop 0
	s_add_u32 s98, s100, s16
	s_addc_u32 s99, s101, s17
	global_load_lds_dwordx4 v128, s[98:99]
	s_mov_b32 m0, s52
	s_nop 0
	s_add_u32 s98, s100, s20
	s_addc_u32 s99, s101, s21
	global_load_lds_dwordx4 v128, s[98:99]
	ds_read_b128 v[174:177], v153 offset:49152
	ds_read_b128 v[178:181], v153 offset:50176
	ds_read_b128 v[182:185], v153 offset:51200
	ds_read_b128 v[186:189], v153 offset:52224
	ds_read_b128 v[190:193], v153 offset:53248
	ds_read_b128 v[194:197], v153 offset:54272
	ds_read_b128 v[198:201], v153 offset:55296
	ds_read_b128 v[202:205], v153 offset:56320
	s_waitcnt vmcnt(8)
	s_waitcnt lgkmcnt(0)
	s_barrier
	s_setprio 1
	s_waitcnt lgkmcnt(0)
	v_mfma_f32_16x16x32_bf16 v[60:63], v[138:141], v[174:177], v[60:63]
	v_mfma_f32_16x16x32_bf16 v[60:63], v[142:145], v[178:181], v[60:63]
	v_mfma_f32_16x16x32_bf16 v[56:59], v[146:149], v[174:177], v[56:59]
	v_mfma_f32_16x16x32_bf16 v[56:59], v[154:157], v[178:181], v[56:59]
	v_mfma_f32_16x16x32_bf16 v[52:55], v[138:141], v[182:185], v[52:55]
	v_mfma_f32_16x16x32_bf16 v[52:55], v[142:145], v[186:189], v[52:55]
	v_mfma_f32_16x16x32_bf16 v[48:51], v[146:149], v[182:185], v[48:51]
	v_mfma_f32_16x16x32_bf16 v[48:51], v[154:157], v[186:189], v[48:51]
	v_mfma_f32_16x16x32_bf16 v[44:47], v[138:141], v[190:193], v[44:47]
	v_mfma_f32_16x16x32_bf16 v[44:47], v[142:145], v[194:197], v[44:47]
	v_mfma_f32_16x16x32_bf16 v[40:43], v[146:149], v[190:193], v[40:43]
	v_mfma_f32_16x16x32_bf16 v[40:43], v[154:157], v[194:197], v[40:43]
	v_mfma_f32_16x16x32_bf16 v[36:39], v[138:141], v[198:201], v[36:39]
	v_mfma_f32_16x16x32_bf16 v[36:39], v[142:145], v[202:205], v[36:39]
	v_mfma_f32_16x16x32_bf16 v[32:35], v[146:149], v[198:201], v[32:35]
	v_mfma_f32_16x16x32_bf16 v[32:35], v[154:157], v[202:205], v[32:35]
	s_setprio 0
	s_setprio 1
	v_mfma_f32_16x16x32_bf16 v[28:31], v[158:161], v[174:177], v[28:31]
	v_mfma_f32_16x16x32_bf16 v[28:31], v[162:165], v[178:181], v[28:31]
	v_mfma_f32_16x16x32_bf16 v[24:27], v[166:169], v[174:177], v[24:27]
	v_mfma_f32_16x16x32_bf16 v[24:27], v[170:173], v[178:181], v[24:27]
	v_mfma_f32_16x16x32_bf16 v[20:23], v[158:161], v[182:185], v[20:23]
	v_mfma_f32_16x16x32_bf16 v[20:23], v[162:165], v[186:189], v[20:23]
	v_mfma_f32_16x16x32_bf16 v[16:19], v[166:169], v[182:185], v[16:19]
	v_mfma_f32_16x16x32_bf16 v[16:19], v[170:173], v[186:189], v[16:19]
	v_mfma_f32_16x16x32_bf16 v[12:15], v[158:161], v[190:193], v[12:15]
	v_mfma_f32_16x16x32_bf16 v[12:15], v[162:165], v[194:197], v[12:15]
	v_mfma_f32_16x16x32_bf16 v[8:11], v[166:169], v[190:193], v[8:11]
	v_mfma_f32_16x16x32_bf16 v[8:11], v[170:173], v[194:197], v[8:11]
	s_setprio 2
	s_barrier
	v_mfma_f32_16x16x32_bf16 v[4:7], v[158:161], v[198:201], v[4:7]
	v_mfma_f32_16x16x32_bf16 v[4:7], v[162:165], v[202:205], v[4:7]
	v_mfma_f32_16x16x32_bf16 v[0:3], v[166:169], v[198:201], v[0:3]
	v_mfma_f32_16x16x32_bf16 v[0:3], v[170:173], v[202:205], v[0:3]
	s_setprio 0
	s_add_i32 s46, s46, 2
	s_add_u32 s62, s62, 0x100
	s_addc_u32 s63, s63, 0
	s_add_u32 s44, s44, 0x100
	s_addc_u32 s45, s45, 0
	s_cmpk_gt_u32 s46, 0xa9
	s_cbranch_scc0 .LBB0_1034
	s_and_b64 vcc, exec, s[38:39]
	s_cbranch_vccz .LBB0_1037
	s_barrier

.LBB0_1180:
	s_add_u32 s49, s46, 0xfff80080
	s_addc_u32 s70, s47, -1
	s_cmp_eq_u32 s48, 28
	s_cselect_b32 s71, s39, s70
	s_cselect_b32 s70, s66, s49
	s_cselect_b32 s73, s37, s69
	s_cselect_b32 s72, s67, s68
	s_add_i32 m0, s45, 0xc000
	s_nop 0
	global_load_lds_dwordx4 v162, s[46:47]
	s_add_i32 m0, s45, 0xe000
	s_nop 0
	s_add_u32 s98, s46, s2
	s_addc_u32 s99, s47, s3
	global_load_lds_dwordx4 v162, s[98:99]
	ds_read_b128 v[112:115], v181
	ds_read_b128 v[116:119], v181 offset:1024
	ds_read_b128 v[128:131], v181 offset:2048
	ds_read_b128 v[142:145], v181 offset:3072
	ds_read_b128 v[146:149], v202
	ds_read_b128 v[150:153], v202 offset:1024
	ds_read_b128 v[154:157], v202 offset:2048
	ds_read_b128 v[168:171], v202 offset:3072
	ds_read_b128 v[172:175], v203
	ds_read_b128 v[182:185], v203 offset:1024
	ds_read_b128 v[186:189], v203 offset:2048
	ds_read_b128 v[190:193], v203 offset:3072
	ds_read_b128 v[194:197], v203 offset:4096
	ds_read_b128 v[198:201], v203 offset:5120
	ds_read_b128 v[206:209], v203 offset:6144
	ds_read_b128 v[210:213], v203 offset:7168
	s_waitcnt vmcnt(8)
	s_waitcnt lgkmcnt(0)
	s_barrier
	s_setprio 1
	s_waitcnt lgkmcnt(0)
	v_mfma_i32_16x16x64_i8 v[138:141], v[112:115], v[172:175], v[138:141]
	v_mfma_i32_16x16x64_i8 v[132:135], v[128:131], v[172:175], v[134:137]
	v_mfma_i32_16x16x64_i8 v[124:127], v[112:115], v[186:189], v[124:127]
	v_mfma_i32_16x16x64_i8 v[120:123], v[128:131], v[186:189], v[120:123]
	v_mfma_i32_16x16x64_i8 v[108:111], v[112:115], v[194:197], v[108:111]
	v_mfma_i32_16x16x64_i8 v[104:107], v[128:131], v[194:197], v[104:107]
	v_mfma_i32_16x16x64_i8 v[100:103], v[112:115], v[206:209], v[100:103]
	v_mfma_i32_16x16x64_i8 v[96:99], v[128:131], v[206:209], v[96:99]
	v_mfma_i32_16x16x64_i8 v[138:141], v[116:119], v[182:185], v[138:141]
	v_mfma_i32_16x16x64_i8 v[132:135], v[142:145], v[182:185], v[132:135]
	v_mfma_i32_16x16x64_i8 v[124:127], v[116:119], v[190:193], v[124:127]
	v_mfma_i32_16x16x64_i8 v[120:123], v[142:145], v[190:193], v[120:123]
	v_mfma_i32_16x16x64_i8 v[108:111], v[116:119], v[198:201], v[108:111]
	v_mfma_i32_16x16x64_i8 v[104:107], v[142:145], v[198:201], v[104:107]
	v_mfma_i32_16x16x64_i8 v[100:103], v[116:119], v[210:213], v[100:103]
	v_mfma_i32_16x16x64_i8 v[96:99], v[142:145], v[210:213], v[96:99]
	s_setprio 0
	s_setprio 1
	v_mfma_i32_16x16x64_i8 v[60:63], v[146:149], v[172:175], v[60:63]
	v_mfma_i32_16x16x64_i8 v[60:63], v[150:153], v[182:185], v[60:63]
	v_mfma_i32_16x16x64_i8 v[56:59], v[154:157], v[172:175], v[56:59]
	v_mfma_i32_16x16x64_i8 v[56:59], v[168:171], v[182:185], v[56:59]
	v_mfma_i32_16x16x64_i8 v[52:55], v[146:149], v[186:189], v[52:55]
	v_mfma_i32_16x16x64_i8 v[52:55], v[150:153], v[190:193], v[52:55]
	v_mfma_i32_16x16x64_i8 v[48:51], v[154:157], v[186:189], v[48:51]
	v_mfma_i32_16x16x64_i8 v[48:51], v[168:171], v[190:193], v[48:51]
	v_mfma_i32_16x16x64_i8 v[44:47], v[146:149], v[194:197], v[44:47]
	v_mfma_i32_16x16x64_i8 v[44:47], v[150:153], v[198:201], v[44:47]
	v_mfma_i32_16x16x64_i8 v[40:43], v[154:157], v[194:197], v[40:43]
	v_mfma_i32_16x16x64_i8 v[40:43], v[168:171], v[198:201], v[40:43]
	s_setprio 2
	s_barrier
	v_mfma_i32_16x16x64_i8 v[36:39], v[146:149], v[206:209], v[36:39]
	v_mfma_i32_16x16x64_i8 v[36:39], v[150:153], v[210:213], v[36:39]
	v_mfma_i32_16x16x64_i8 v[32:35], v[154:157], v[206:209], v[32:35]
	v_mfma_i32_16x16x64_i8 v[32:35], v[168:171], v[210:213], v[32:35]
	s_setprio 0
	s_add_i32 s49, s61, s33
	s_mov_b32 m0, s49
	s_nop 0
	global_load_lds_dwordx4 v160, s[72:73]
	s_add_i32 m0, s49, 0x2000
	s_add_i32 s49, s62, s33
	s_add_u32 s98, s72, s2
	s_addc_u32 s99, s73, s3
	global_load_lds_dwordx4 v160, s[98:99]
	s_mov_b32 m0, s49
	s_mov_b64 s[100:101], s[70:71]
	s_add_u32 s98, s72, s6
	s_addc_u32 s99, s73, s7
	global_load_lds_dwordx4 v160, s[98:99]
	s_add_i32 m0, s49, 0x2000
	s_nop 0
	s_add_u32 s98, s72, s8
	s_addc_u32 s99, s73, s9
	global_load_lds_dwordx4 v160, s[98:99]
	s_mov_b32 m0, s45
	s_nop 0
	global_load_lds_dwordx4 v158, s[70:71]
	s_mov_b32 m0, s50
	s_nop 0
	s_add_u32 s98, s70, s2
	s_addc_u32 s99, s71, s3
	global_load_lds_dwordx4 v158, s[98:99]
	ds_read_b128 v[172:175], v203 offset:16384
	ds_read_b128 v[182:185], v203 offset:17408
	ds_read_b128 v[186:189], v203 offset:18432
	ds_read_b128 v[190:193], v203 offset:19456
	ds_read_b128 v[194:197], v203 offset:20480
	ds_read_b128 v[198:201], v203 offset:21504
	ds_read_b128 v[206:209], v203 offset:22528
	ds_read_b128 v[210:213], v203 offset:23552
	s_waitcnt vmcnt(8)
	s_waitcnt lgkmcnt(0)
	s_barrier
	s_setprio 1
	s_waitcnt lgkmcnt(0)
	v_mfma_i32_16x16x64_i8 v[92:95], v[112:115], v[172:175], v[92:95]
	v_mfma_i32_16x16x64_i8 v[92:95], v[116:119], v[182:185], v[92:95]
	v_mfma_i32_16x16x64_i8 v[88:91], v[128:131], v[172:175], v[88:91]
	v_mfma_i32_16x16x64_i8 v[88:91], v[142:145], v[182:185], v[88:91]
	v_mfma_i32_16x16x64_i8 v[84:87], v[112:115], v[186:189], v[84:87]
	v_mfma_i32_16x16x64_i8 v[84:87], v[116:119], v[190:193], v[84:87]
	v_mfma_i32_16x16x64_i8 v[80:83], v[128:131], v[186:189], v[80:83]
	v_mfma_i32_16x16x64_i8 v[80:83], v[142:145], v[190:193], v[80:83]
	v_mfma_i32_16x16x64_i8 v[76:79], v[112:115], v[194:197], v[76:79]
	v_mfma_i32_16x16x64_i8 v[76:79], v[116:119], v[198:201], v[76:79]
	v_mfma_i32_16x16x64_i8 v[72:75], v[128:131], v[194:197], v[72:75]
	v_mfma_i32_16x16x64_i8 v[72:75], v[142:145], v[198:201], v[72:75]
	v_mfma_i32_16x16x64_i8 v[68:71], v[112:115], v[206:209], v[68:71]
	v_mfma_i32_16x16x64_i8 v[68:71], v[116:119], v[210:213], v[68:71]
	v_mfma_i32_16x16x64_i8 v[64:67], v[128:131], v[206:209], v[64:67]
	v_mfma_i32_16x16x64_i8 v[64:67], v[142:145], v[210:213], v[64:67]
	s_setprio 0
	s_setprio 1
	v_mfma_i32_16x16x64_i8 v[28:31], v[146:149], v[172:175], v[28:31]
	v_mfma_i32_16x16x64_i8 v[28:31], v[150:153], v[182:185], v[28:31]
	v_mfma_i32_16x16x64_i8 v[24:27], v[154:157], v[172:175], v[24:27]
	v_mfma_i32_16x16x64_i8 v[24:27], v[168:171], v[182:185], v[24:27]
	v_mfma_i32_16x16x64_i8 v[20:23], v[146:149], v[186:189], v[20:23]
	v_mfma_i32_16x16x64_i8 v[20:23], v[150:153], v[190:193], v[20:23]
	v_mfma_i32_16x16x64_i8 v[16:19], v[154:157], v[186:189], v[16:19]
	v_mfma_i32_16x16x64_i8 v[16:19], v[168:171], v[190:193], v[16:19]
	v_mfma_i32_16x16x64_i8 v[12:15], v[146:149], v[194:197], v[12:15]
	v_mfma_i32_16x16x64_i8 v[12:15], v[150:153], v[198:201], v[12:15]
	v_mfma_i32_16x16x64_i8 v[8:11], v[154:157], v[194:197], v[8:11]
	v_mfma_i32_16x16x64_i8 v[8:11], v[168:171], v[198:201], v[8:11]
	s_setprio 2
	s_barrier
	v_mfma_i32_16x16x64_i8 v[4:7], v[146:149], v[206:209], v[4:7]
	v_mfma_i32_16x16x64_i8 v[4:7], v[150:153], v[210:213], v[4:7]
	v_mfma_i32_16x16x64_i8 v[0:3], v[154:157], v[206:209], v[0:3]
	v_mfma_i32_16x16x64_i8 v[0:3], v[168:171], v[210:213], v[0:3]
	s_setprio 0
	s_mov_b32 m0, s51
	s_add_u32 s98, s100, s6
	s_addc_u32 s99, s101, s7
	global_load_lds_dwordx4 v158, s[98:99]
	s_mov_b32 m0, s52
	s_nop 0
	s_add_u32 s98, s100, s8
	s_addc_u32 s99, s101, s9
	global_load_lds_dwordx4 v158, s[98:99]
	s_add_i32 s49, 0, 0x18000
	v_add_u32_e32 v136, s49, v179
	s_add_i32 s70, 0, 0x1c000
	ds_read_b128 v[112:115], v136
	ds_read_b128 v[116:119], v136 offset:1024
	ds_read_b128 v[128:131], v136 offset:2048
	ds_read_b128 v[142:145], v136 offset:3072
	v_add_u32_e32 v136, s70, v179
	ds_read_b128 v[146:149], v136
	ds_read_b128 v[150:153], v136 offset:1024
	ds_read_b128 v[154:157], v136 offset:2048
	ds_read_b128 v[168:171], v136 offset:3072
	ds_read_b128 v[172:175], v203 offset:32768
	ds_read_b128 v[182:185], v203 offset:33792
	ds_read_b128 v[186:189], v203 offset:34816
	ds_read_b128 v[190:193], v203 offset:35840
	ds_read_b128 v[194:197], v203 offset:36864
	ds_read_b128 v[198:201], v203 offset:37888
	ds_read_b128 v[206:209], v203 offset:38912
	ds_read_b128 v[210:213], v203 offset:39936
	s_waitcnt vmcnt(8)
	s_waitcnt lgkmcnt(0)
	s_barrier
	s_setprio 1
	s_waitcnt lgkmcnt(0)
	v_mfma_i32_16x16x64_i8 v[136:139], v[112:115], v[172:175], v[138:141]
	v_mfma_i32_16x16x64_i8 v[132:135], v[128:131], v[172:175], v[132:135]
	v_mfma_i32_16x16x64_i8 v[124:127], v[112:115], v[186:189], v[124:127]
	v_mfma_i32_16x16x64_i8 v[120:123], v[128:131], v[186:189], v[120:123]
	v_mfma_i32_16x16x64_i8 v[108:111], v[112:115], v[194:197], v[108:111]
	v_mfma_i32_16x16x64_i8 v[104:107], v[128:131], v[194:197], v[104:107]
	v_mfma_i32_16x16x64_i8 v[100:103], v[112:115], v[206:209], v[100:103]
	v_mfma_i32_16x16x64_i8 v[96:99], v[128:131], v[206:209], v[96:99]
	v_mfma_i32_16x16x64_i8 v[138:141], v[116:119], v[182:185], v[136:139]
	v_mfma_i32_16x16x64_i8 v[134:137], v[142:145], v[182:185], v[132:135]
	v_mfma_i32_16x16x64_i8 v[124:127], v[116:119], v[190:193], v[124:127]
	v_mfma_i32_16x16x64_i8 v[120:123], v[142:145], v[190:193], v[120:123]
	v_mfma_i32_16x16x64_i8 v[108:111], v[116:119], v[198:201], v[108:111]
	v_mfma_i32_16x16x64_i8 v[104:107], v[142:145], v[198:201], v[104:107]
	v_mfma_i32_16x16x64_i8 v[100:103], v[116:119], v[210:213], v[100:103]
	v_mfma_i32_16x16x64_i8 v[96:99], v[142:145], v[210:213], v[96:99]
	s_setprio 0
	s_setprio 1
	v_mfma_i32_16x16x64_i8 v[60:63], v[146:149], v[172:175], v[60:63]
	v_mfma_i32_16x16x64_i8 v[60:63], v[150:153], v[182:185], v[60:63]
	v_mfma_i32_16x16x64_i8 v[56:59], v[154:157], v[172:175], v[56:59]
	v_mfma_i32_16x16x64_i8 v[56:59], v[168:171], v[182:185], v[56:59]
	v_mfma_i32_16x16x64_i8 v[52:55], v[146:149], v[186:189], v[52:55]
	v_mfma_i32_16x16x64_i8 v[52:55], v[150:153], v[190:193], v[52:55]
	v_mfma_i32_16x16x64_i8 v[48:51], v[154:157], v[186:189], v[48:51]
	v_mfma_i32_16x16x64_i8 v[48:51], v[168:171], v[190:193], v[48:51]
	v_mfma_i32_16x16x64_i8 v[44:47], v[146:149], v[194:197], v[44:47]
	v_mfma_i32_16x16x64_i8 v[44:47], v[150:153], v[198:201], v[44:47]
	v_mfma_i32_16x16x64_i8 v[40:43], v[154:157], v[194:197], v[40:43]
	v_mfma_i32_16x16x64_i8 v[40:43], v[168:171], v[198:201], v[40:43]
	s_setprio 2
	s_barrier
	v_mfma_i32_16x16x64_i8 v[36:39], v[146:149], v[206:209], v[36:39]
	v_mfma_i32_16x16x64_i8 v[36:39], v[150:153], v[210:213], v[36:39]
	v_mfma_i32_16x16x64_i8 v[32:35], v[154:157], v[206:209], v[32:35]
	v_mfma_i32_16x16x64_i8 v[32:35], v[168:171], v[210:213], v[32:35]
	s_setprio 0
	s_add_i32 s49, s49, s33
	s_mov_b32 m0, s49
	s_add_u32 s98, s72, s16
	s_addc_u32 s99, s73, s17
	global_load_lds_dwordx4 v160, s[98:99]
	s_add_i32 m0, s49, 0x2000
	s_add_i32 s49, s70, s33
	s_add_u32 s98, s72, s18
	s_addc_u32 s99, s73, s19
	global_load_lds_dwordx4 v160, s[98:99]
	s_mov_b32 m0, s49
	s_nop 0
	s_add_u32 s98, s72, s20
	s_addc_u32 s99, s73, s21
	global_load_lds_dwordx4 v160, s[98:99]
	s_add_i32 m0, s49, 0x2000
	s_nop 0
	s_add_u32 s98, s72, s30
	s_addc_u32 s99, s73, s31
	global_load_lds_dwordx4 v160, s[98:99]
	s_mov_b32 m0, s54
	s_nop 0
	s_add_u32 s98, s100, s16
	s_addc_u32 s99, s101, s17
	global_load_lds_dwordx4 v158, s[98:99]
	s_mov_b32 m0, s55
	s_nop 0
	s_add_u32 s98, s100, s18
	s_addc_u32 s99, s101, s19
	global_load_lds_dwordx4 v158, s[98:99]
	ds_read_b128 v[172:175], v203 offset:49152
	ds_read_b128 v[182:185], v203 offset:50176
	ds_read_b128 v[186:189], v203 offset:51200
	ds_read_b128 v[190:193], v203 offset:52224
	ds_read_b128 v[194:197], v203 offset:53248
	ds_read_b128 v[198:201], v203 offset:54272
	ds_read_b128 v[206:209], v203 offset:55296
	ds_read_b128 v[210:213], v203 offset:56320
	s_waitcnt vmcnt(8)
	s_waitcnt lgkmcnt(0)
	s_barrier
	s_setprio 1
	s_waitcnt lgkmcnt(0)
	v_mfma_i32_16x16x64_i8 v[92:95], v[112:115], v[172:175], v[92:95]
	v_mfma_i32_16x16x64_i8 v[92:95], v[116:119], v[182:185], v[92:95]
	v_mfma_i32_16x16x64_i8 v[88:91], v[128:131], v[172:175], v[88:91]
	v_mfma_i32_16x16x64_i8 v[88:91], v[142:145], v[182:185], v[88:91]
	v_mfma_i32_16x16x64_i8 v[84:87], v[112:115], v[186:189], v[84:87]
	v_mfma_i32_16x16x64_i8 v[84:87], v[116:119], v[190:193], v[84:87]
	v_mfma_i32_16x16x64_i8 v[80:83], v[128:131], v[186:189], v[80:83]
	v_mfma_i32_16x16x64_i8 v[80:83], v[142:145], v[190:193], v[80:83]
	v_mfma_i32_16x16x64_i8 v[76:79], v[112:115], v[194:197], v[76:79]
	v_mfma_i32_16x16x64_i8 v[76:79], v[116:119], v[198:201], v[76:79]
	v_mfma_i32_16x16x64_i8 v[72:75], v[128:131], v[194:197], v[72:75]
	v_mfma_i32_16x16x64_i8 v[72:75], v[142:145], v[198:201], v[72:75]
	v_mfma_i32_16x16x64_i8 v[68:71], v[112:115], v[206:209], v[68:71]
	v_mfma_i32_16x16x64_i8 v[68:71], v[116:119], v[210:213], v[68:71]
	v_mfma_i32_16x16x64_i8 v[64:67], v[128:131], v[206:209], v[64:67]
	v_mfma_i32_16x16x64_i8 v[64:67], v[142:145], v[210:213], v[64:67]
	s_setprio 0
	s_setprio 1
	v_mfma_i32_16x16x64_i8 v[28:31], v[146:149], v[172:175], v[28:31]
	v_mfma_i32_16x16x64_i8 v[28:31], v[150:153], v[182:185], v[28:31]
	v_mfma_i32_16x16x64_i8 v[24:27], v[154:157], v[172:175], v[24:27]
	v_mfma_i32_16x16x64_i8 v[24:27], v[168:171], v[182:185], v[24:27]
	v_mfma_i32_16x16x64_i8 v[20:23], v[146:149], v[186:189], v[20:23]
	v_mfma_i32_16x16x64_i8 v[20:23], v[150:153], v[190:193], v[20:23]
	v_mfma_i32_16x16x64_i8 v[16:19], v[154:157], v[186:189], v[16:19]
	v_mfma_i32_16x16x64_i8 v[16:19], v[168:171], v[190:193], v[16:19]
	v_mfma_i32_16x16x64_i8 v[12:15], v[146:149], v[194:197], v[12:15]
	v_mfma_i32_16x16x64_i8 v[12:15], v[150:153], v[198:201], v[12:15]
	v_mfma_i32_16x16x64_i8 v[8:11], v[154:157], v[194:197], v[8:11]
	v_mfma_i32_16x16x64_i8 v[8:11], v[168:171], v[198:201], v[8:11]
	s_setprio 2
	s_barrier
	v_mfma_i32_16x16x64_i8 v[4:7], v[146:149], v[206:209], v[4:7]
	v_mfma_i32_16x16x64_i8 v[4:7], v[150:153], v[210:213], v[4:7]
	v_mfma_i32_16x16x64_i8 v[0:3], v[154:157], v[206:209], v[0:3]
	v_mfma_i32_16x16x64_i8 v[0:3], v[168:171], v[210:213], v[0:3]
	s_setprio 0
	s_add_i32 s48, s48, 2
	s_add_u32 s68, s68, 0x100
	s_addc_u32 s69, s69, 0
	s_add_u32 s46, s46, 0x100
	s_addc_u32 s47, s47, 0
	s_cmp_gt_u32 s48, 29
	s_cbranch_scc0 .LBB0_1180
	s_and_b64 vcc, exec, s[34:35]
	s_cbranch_vccz .LBB0_1183
	s_barrier
